# GEMM loops: s_nop 3 between the block-opening barrier and the first MFMA of each 32-MFMA block (20 sites)
# speedup vs baseline: 1.0005x; 1.0005x over previous
.LBB0_177:
	ds_read_b128 v[128:131], v171
	ds_read_b128 v[132:135], v171 offset:1024
	ds_read_b128 v[136:139], v171 offset:2048
	ds_read_b128 v[160:163], v171 offset:3072
	ds_read_b128 v[164:167], v172
	ds_read_b128 v[174:177], v172 offset:1024
	ds_read_b128 v[178:181], v172 offset:2048
	ds_read_b128 v[182:185], v172 offset:3072
	s_add_u32 s52, s44, 0xfffc0080
	s_addc_u32 s53, s45, -1
	s_cmp_eq_u32 s84, 12
	s_cselect_b32 s57, s7, s53
	s_cselect_b32 s56, s8, s52
	s_cselect_b32 s53, s27, s83
	s_cselect_b32 s52, s29, s43
	v_lshl_add_u64 v[198:199], s[44:45], 0, v[152:153]
	s_add_i32 m0, s33, 0xc000
	ds_read_b128 v[186:189], v173
	ds_read_b128 v[190:193], v173 offset:1024
	ds_read_b128 v[194:197], v173 offset:2048
	ds_read_b128 v[202:205], v173 offset:3072
	ds_read_b128 v[206:209], v173 offset:4096
	ds_read_b128 v[210:213], v173 offset:5120
	ds_read_b128 v[214:217], v173 offset:6144
	ds_read_b128 v[218:221], v173 offset:7168
	global_load_lds_dwordx4 v[198:199], off
	s_add_i32 m0, s33, 0xe000
	v_lshl_add_u64 v[198:199], s[44:45], 0, v[154:155]
	global_load_lds_dwordx4 v[198:199], off
	s_waitcnt vmcnt(8)
	s_waitcnt lgkmcnt(0)
	s_barrier
	s_waitcnt lgkmcnt(0)
	s_nop 3
	v_mfma_f32_16x16x32_bf16 v[124:127], v[128:131], v[186:189], v[124:127]
	v_mfma_f32_16x16x32_bf16 v[120:123], v[136:139], v[186:189], v[120:123]
	v_mfma_f32_16x16x32_bf16 v[112:115], v[128:131], v[194:197], v[112:115]
	v_mfma_f32_16x16x32_bf16 v[104:107], v[136:139], v[194:197], v[104:107]
	v_mfma_f32_16x16x32_bf16 v[100:103], v[128:131], v[206:209], v[100:103]
	v_mfma_f32_16x16x32_bf16 v[92:95], v[136:139], v[206:209], v[92:95]
	v_mfma_f32_16x16x32_bf16 v[84:87], v[128:131], v[214:217], v[84:87]
	v_mfma_f32_16x16x32_bf16 v[76:79], v[136:139], v[214:217], v[76:79]
	v_mfma_f32_16x16x32_bf16 v[124:127], v[132:135], v[190:193], v[124:127]
	v_mfma_f32_16x16x32_bf16 v[120:123], v[160:163], v[190:193], v[120:123]
	v_mfma_f32_16x16x32_bf16 v[112:115], v[132:135], v[202:205], v[112:115]
	v_mfma_f32_16x16x32_bf16 v[104:107], v[160:163], v[202:205], v[104:107]
	v_mfma_f32_16x16x32_bf16 v[100:103], v[132:135], v[210:213], v[100:103]
	v_mfma_f32_16x16x32_bf16 v[92:95], v[160:163], v[210:213], v[92:95]
	v_mfma_f32_16x16x32_bf16 v[84:87], v[132:135], v[218:221], v[84:87]
	v_mfma_f32_16x16x32_bf16 v[76:79], v[160:163], v[218:221], v[76:79]
	v_mfma_f32_16x16x32_bf16 v[116:119], v[164:167], v[186:189], v[116:119]
	v_mfma_f32_16x16x32_bf16 v[108:111], v[178:181], v[186:189], v[108:111]
	v_mfma_f32_16x16x32_bf16 v[96:99], v[164:167], v[194:197], v[96:99]
	v_mfma_f32_16x16x32_bf16 v[88:91], v[178:181], v[194:197], v[88:91]
	v_mfma_f32_16x16x32_bf16 v[80:83], v[164:167], v[206:209], v[80:83]
	v_mfma_f32_16x16x32_bf16 v[72:75], v[178:181], v[206:209], v[72:75]
	v_mfma_f32_16x16x32_bf16 v[68:71], v[164:167], v[214:217], v[68:71]
	v_mfma_f32_16x16x32_bf16 v[64:67], v[178:181], v[214:217], v[64:67]
	v_mfma_f32_16x16x32_bf16 v[116:119], v[174:177], v[190:193], v[116:119]
	v_mfma_f32_16x16x32_bf16 v[108:111], v[182:185], v[190:193], v[108:111]
	v_mfma_f32_16x16x32_bf16 v[96:99], v[174:177], v[202:205], v[96:99]
	v_mfma_f32_16x16x32_bf16 v[88:91], v[182:185], v[202:205], v[88:91]
	v_mfma_f32_16x16x32_bf16 v[80:83], v[174:177], v[210:213], v[80:83]
	v_mfma_f32_16x16x32_bf16 v[72:75], v[182:185], v[210:213], v[72:75]
	v_mfma_f32_16x16x32_bf16 v[68:71], v[174:177], v[218:221], v[68:71]
	v_mfma_f32_16x16x32_bf16 v[64:67], v[182:185], v[218:221], v[64:67]
	s_barrier
	s_add_i32 s85, s80, s3
	v_lshl_add_u64 v[198:199], s[52:53], 0, v[142:143]
	s_mov_b32 m0, s85
	ds_read_b128 v[186:189], v173 offset:16384
	ds_read_b128 v[190:193], v173 offset:17408
	ds_read_b128 v[194:197], v173 offset:18432
	ds_read_b128 v[202:205], v173 offset:19456
	ds_read_b128 v[206:209], v173 offset:20480
	ds_read_b128 v[210:213], v173 offset:21504
	ds_read_b128 v[214:217], v173 offset:22528
	ds_read_b128 v[218:221], v173 offset:23552
	global_load_lds_dwordx4 v[198:199], off
	s_add_i32 m0, s85, 0x2000
	s_add_u32 s86, s52, 0x40000
	v_lshl_add_u64 v[200:201], s[52:53], 0, v[146:147]
	s_addc_u32 s87, s53, 0
	s_add_i32 s85, s81, s3
	global_load_lds_dwordx4 v[200:201], off
	v_lshl_add_u64 v[222:223], s[86:87], 0, v[142:143]
	s_mov_b32 m0, s85
	v_lshl_add_u64 v[224:225], s[56:57], 0, v[144:145]
	global_load_lds_dwordx4 v[222:223], off
	s_add_i32 m0, s85, 0x2000
	v_lshl_add_u64 v[222:223], s[86:87], 0, v[146:147]
	global_load_lds_dwordx4 v[222:223], off
	s_mov_b32 m0, s33
	v_lshl_add_u64 v[222:223], s[56:57], 0, v[140:141]
	global_load_lds_dwordx4 v[222:223], off
	s_mov_b32 m0, s62
	s_nop 0
	global_load_lds_dwordx4 v[224:225], off
	s_waitcnt vmcnt(8)
	s_waitcnt lgkmcnt(0)
	s_barrier
	s_waitcnt lgkmcnt(0)
	s_nop 3
	v_mfma_f32_16x16x32_bf16 v[60:63], v[128:131], v[186:189], v[60:63]
	v_mfma_f32_16x16x32_bf16 v[56:59], v[136:139], v[186:189], v[56:59]
	v_mfma_f32_16x16x32_bf16 v[52:55], v[128:131], v[194:197], v[52:55]
	v_mfma_f32_16x16x32_bf16 v[44:47], v[136:139], v[194:197], v[44:47]
	v_mfma_f32_16x16x32_bf16 v[36:39], v[128:131], v[206:209], v[36:39]
	v_mfma_f32_16x16x32_bf16 v[28:31], v[136:139], v[206:209], v[28:31]
	v_mfma_f32_16x16x32_bf16 v[20:23], v[128:131], v[214:217], v[20:23]
	v_mfma_f32_16x16x32_bf16 v[12:15], v[136:139], v[214:217], v[12:15]
	v_mfma_f32_16x16x32_bf16 v[60:63], v[132:135], v[190:193], v[60:63]
	v_mfma_f32_16x16x32_bf16 v[56:59], v[160:163], v[190:193], v[56:59]
	v_mfma_f32_16x16x32_bf16 v[52:55], v[132:135], v[202:205], v[52:55]
	v_mfma_f32_16x16x32_bf16 v[44:47], v[160:163], v[202:205], v[44:47]
	v_mfma_f32_16x16x32_bf16 v[36:39], v[132:135], v[210:213], v[36:39]
	v_mfma_f32_16x16x32_bf16 v[28:31], v[160:163], v[210:213], v[28:31]
	v_mfma_f32_16x16x32_bf16 v[20:23], v[132:135], v[218:221], v[20:23]
	v_mfma_f32_16x16x32_bf16 v[12:15], v[160:163], v[218:221], v[12:15]
	v_mfma_f32_16x16x32_bf16 v[48:51], v[164:167], v[186:189], v[48:51]
	v_mfma_f32_16x16x32_bf16 v[40:43], v[178:181], v[186:189], v[40:43]
	v_mfma_f32_16x16x32_bf16 v[32:35], v[164:167], v[194:197], v[32:35]
	v_mfma_f32_16x16x32_bf16 v[24:27], v[178:181], v[194:197], v[24:27]
	v_mfma_f32_16x16x32_bf16 v[16:19], v[164:167], v[206:209], v[16:19]
	v_mfma_f32_16x16x32_bf16 v[8:11], v[178:181], v[206:209], v[8:11]
	v_mfma_f32_16x16x32_bf16 v[4:7], v[164:167], v[214:217], v[4:7]
	v_mfma_f32_16x16x32_bf16 v[0:3], v[178:181], v[214:217], v[0:3]
	v_mfma_f32_16x16x32_bf16 v[48:51], v[174:177], v[190:193], v[48:51]
	v_mfma_f32_16x16x32_bf16 v[40:43], v[182:185], v[190:193], v[40:43]
	v_mfma_f32_16x16x32_bf16 v[32:35], v[174:177], v[202:205], v[32:35]
	v_mfma_f32_16x16x32_bf16 v[24:27], v[182:185], v[202:205], v[24:27]
	v_mfma_f32_16x16x32_bf16 v[16:19], v[174:177], v[210:213], v[16:19]
	v_mfma_f32_16x16x32_bf16 v[8:11], v[182:185], v[210:213], v[8:11]
	v_mfma_f32_16x16x32_bf16 v[4:7], v[174:177], v[218:221], v[4:7]
	v_mfma_f32_16x16x32_bf16 v[0:3], v[182:185], v[218:221], v[0:3]
	s_barrier
	s_add_i32 s85, 0, 0x18000
	v_add_u32_e32 v148, s85, v169
	s_add_i32 s86, 0, 0x1c000
	ds_read_b128 v[128:131], v148
	ds_read_b128 v[132:135], v148 offset:1024
	ds_read_b128 v[136:139], v148 offset:2048
	ds_read_b128 v[160:163], v148 offset:3072
	v_add_u32_e32 v148, s86, v169
	ds_read_b128 v[164:167], v148
	ds_read_b128 v[174:177], v148 offset:1024
	ds_read_b128 v[178:181], v148 offset:2048
	ds_read_b128 v[182:185], v148 offset:3072
	s_add_u32 s56, s56, 0x40000
	s_addc_u32 s57, s57, 0
	s_mov_b32 m0, s63
	v_lshl_add_u64 v[226:227], s[56:57], 0, v[140:141]
	ds_read_b128 v[186:189], v173 offset:32768
	ds_read_b128 v[190:193], v173 offset:33792
	ds_read_b128 v[194:197], v173 offset:34816
	ds_read_b128 v[202:205], v173 offset:35840
	ds_read_b128 v[206:209], v173 offset:36864
	ds_read_b128 v[210:213], v173 offset:37888
	ds_read_b128 v[214:217], v173 offset:38912
	ds_read_b128 v[218:221], v173 offset:39936
	global_load_lds_dwordx4 v[226:227], off
	s_mov_b32 m0, s64
	v_lshl_add_u64 v[226:227], s[56:57], 0, v[144:145]
	global_load_lds_dwordx4 v[226:227], off
	s_waitcnt vmcnt(8)
	s_waitcnt lgkmcnt(0)
	s_barrier
	s_waitcnt lgkmcnt(0)
	s_nop 3
	v_mfma_f32_16x16x32_bf16 v[124:127], v[128:131], v[186:189], v[124:127]
	v_mfma_f32_16x16x32_bf16 v[120:123], v[136:139], v[186:189], v[120:123]
	v_mfma_f32_16x16x32_bf16 v[112:115], v[128:131], v[194:197], v[112:115]
	v_mfma_f32_16x16x32_bf16 v[104:107], v[136:139], v[194:197], v[104:107]
	v_mfma_f32_16x16x32_bf16 v[100:103], v[128:131], v[206:209], v[100:103]
	v_mfma_f32_16x16x32_bf16 v[92:95], v[136:139], v[206:209], v[92:95]
	v_mfma_f32_16x16x32_bf16 v[84:87], v[128:131], v[214:217], v[84:87]
	v_mfma_f32_16x16x32_bf16 v[76:79], v[136:139], v[214:217], v[76:79]
	v_mfma_f32_16x16x32_bf16 v[124:127], v[132:135], v[190:193], v[124:127]
	v_mfma_f32_16x16x32_bf16 v[120:123], v[160:163], v[190:193], v[120:123]
	v_mfma_f32_16x16x32_bf16 v[112:115], v[132:135], v[202:205], v[112:115]
	v_mfma_f32_16x16x32_bf16 v[104:107], v[160:163], v[202:205], v[104:107]
	v_mfma_f32_16x16x32_bf16 v[100:103], v[132:135], v[210:213], v[100:103]
	v_mfma_f32_16x16x32_bf16 v[92:95], v[160:163], v[210:213], v[92:95]
	v_mfma_f32_16x16x32_bf16 v[84:87], v[132:135], v[218:221], v[84:87]
	v_mfma_f32_16x16x32_bf16 v[76:79], v[160:163], v[218:221], v[76:79]
	v_mfma_f32_16x16x32_bf16 v[116:119], v[164:167], v[186:189], v[116:119]
	v_mfma_f32_16x16x32_bf16 v[108:111], v[178:181], v[186:189], v[108:111]
	v_mfma_f32_16x16x32_bf16 v[96:99], v[164:167], v[194:197], v[96:99]
	v_mfma_f32_16x16x32_bf16 v[88:91], v[178:181], v[194:197], v[88:91]
	v_mfma_f32_16x16x32_bf16 v[80:83], v[164:167], v[206:209], v[80:83]
	v_mfma_f32_16x16x32_bf16 v[72:75], v[178:181], v[206:209], v[72:75]
	v_mfma_f32_16x16x32_bf16 v[68:71], v[164:167], v[214:217], v[68:71]
	v_mfma_f32_16x16x32_bf16 v[64:67], v[178:181], v[214:217], v[64:67]
	v_mfma_f32_16x16x32_bf16 v[116:119], v[174:177], v[190:193], v[116:119]
	v_mfma_f32_16x16x32_bf16 v[108:111], v[182:185], v[190:193], v[108:111]
	v_mfma_f32_16x16x32_bf16 v[96:99], v[174:177], v[202:205], v[96:99]
	v_mfma_f32_16x16x32_bf16 v[88:91], v[182:185], v[202:205], v[88:91]
	v_mfma_f32_16x16x32_bf16 v[80:83], v[174:177], v[210:213], v[80:83]
	v_mfma_f32_16x16x32_bf16 v[72:75], v[182:185], v[210:213], v[72:75]
	v_mfma_f32_16x16x32_bf16 v[68:71], v[174:177], v[218:221], v[68:71]
	v_mfma_f32_16x16x32_bf16 v[64:67], v[182:185], v[218:221], v[64:67]
	s_barrier
	s_add_i32 s56, s85, s3
	v_lshl_add_u64 v[198:199], v[198:199], 0, s[16:17]
	s_mov_b32 m0, s56
	ds_read_b128 v[186:189], v173 offset:49152
	ds_read_b128 v[190:193], v173 offset:50176
	ds_read_b128 v[194:197], v173 offset:51200
	ds_read_b128 v[202:205], v173 offset:52224
	ds_read_b128 v[206:209], v173 offset:53248
	ds_read_b128 v[210:213], v173 offset:54272
	ds_read_b128 v[214:217], v173 offset:55296
	ds_read_b128 v[218:221], v173 offset:56320
	global_load_lds_dwordx4 v[198:199], off
	s_add_i32 m0, s56, 0x2000
	s_add_u32 s52, s52, 0x40080
	v_lshl_add_u64 v[198:199], v[200:201], 0, s[16:17]
	s_addc_u32 s53, s53, 0
	s_add_i32 s56, s86, s3
	global_load_lds_dwordx4 v[198:199], off
	s_mov_b32 m0, s56
	v_lshl_add_u64 v[198:199], s[52:53], 0, v[142:143]
	global_load_lds_dwordx4 v[198:199], off
	s_add_i32 m0, s56, 0x2000
	v_lshl_add_u64 v[198:199], s[52:53], 0, v[146:147]
	global_load_lds_dwordx4 v[198:199], off
	s_mov_b32 m0, s69
	v_lshl_add_u64 v[198:199], v[222:223], 0, s[16:17]
	global_load_lds_dwordx4 v[198:199], off
	s_mov_b32 m0, s72
	v_lshl_add_u64 v[198:199], v[224:225], 0, s[16:17]
	global_load_lds_dwordx4 v[198:199], off
	s_waitcnt vmcnt(8)
	s_waitcnt lgkmcnt(0)
	s_barrier
	s_waitcnt lgkmcnt(0)
	s_nop 3
	v_mfma_f32_16x16x32_bf16 v[60:63], v[128:131], v[186:189], v[60:63]
	v_mfma_f32_16x16x32_bf16 v[56:59], v[136:139], v[186:189], v[56:59]
	v_mfma_f32_16x16x32_bf16 v[52:55], v[128:131], v[194:197], v[52:55]
	v_mfma_f32_16x16x32_bf16 v[44:47], v[136:139], v[194:197], v[44:47]
	v_mfma_f32_16x16x32_bf16 v[36:39], v[128:131], v[206:209], v[36:39]
	v_mfma_f32_16x16x32_bf16 v[28:31], v[136:139], v[206:209], v[28:31]
	v_mfma_f32_16x16x32_bf16 v[20:23], v[128:131], v[214:217], v[20:23]
	v_mfma_f32_16x16x32_bf16 v[12:15], v[136:139], v[214:217], v[12:15]
	v_mfma_f32_16x16x32_bf16 v[60:63], v[132:135], v[190:193], v[60:63]
	v_mfma_f32_16x16x32_bf16 v[56:59], v[160:163], v[190:193], v[56:59]
	v_mfma_f32_16x16x32_bf16 v[52:55], v[132:135], v[202:205], v[52:55]
	v_mfma_f32_16x16x32_bf16 v[44:47], v[160:163], v[202:205], v[44:47]
	v_mfma_f32_16x16x32_bf16 v[36:39], v[132:135], v[210:213], v[36:39]
	v_mfma_f32_16x16x32_bf16 v[28:31], v[160:163], v[210:213], v[28:31]
	v_mfma_f32_16x16x32_bf16 v[20:23], v[132:135], v[218:221], v[20:23]
	v_mfma_f32_16x16x32_bf16 v[12:15], v[160:163], v[218:221], v[12:15]
	v_mfma_f32_16x16x32_bf16 v[48:51], v[164:167], v[186:189], v[48:51]
	v_mfma_f32_16x16x32_bf16 v[40:43], v[178:181], v[186:189], v[40:43]
	v_mfma_f32_16x16x32_bf16 v[32:35], v[164:167], v[194:197], v[32:35]
	v_mfma_f32_16x16x32_bf16 v[24:27], v[178:181], v[194:197], v[24:27]
	v_mfma_f32_16x16x32_bf16 v[16:19], v[164:167], v[206:209], v[16:19]
	v_mfma_f32_16x16x32_bf16 v[8:11], v[178:181], v[206:209], v[8:11]
	v_mfma_f32_16x16x32_bf16 v[4:7], v[164:167], v[214:217], v[4:7]
	v_mfma_f32_16x16x32_bf16 v[0:3], v[178:181], v[214:217], v[0:3]
	v_mfma_f32_16x16x32_bf16 v[48:51], v[174:177], v[190:193], v[48:51]
	v_mfma_f32_16x16x32_bf16 v[40:43], v[182:185], v[190:193], v[40:43]
	v_mfma_f32_16x16x32_bf16 v[32:35], v[174:177], v[202:205], v[32:35]
	v_mfma_f32_16x16x32_bf16 v[24:27], v[182:185], v[202:205], v[24:27]
	v_mfma_f32_16x16x32_bf16 v[16:19], v[174:177], v[210:213], v[16:19]
	v_mfma_f32_16x16x32_bf16 v[8:11], v[182:185], v[210:213], v[8:11]
	v_mfma_f32_16x16x32_bf16 v[4:7], v[174:177], v[218:221], v[4:7]
	v_mfma_f32_16x16x32_bf16 v[0:3], v[182:185], v[218:221], v[0:3]
	s_barrier
	s_add_i32 s84, s84, 2
	s_add_u32 s44, s44, 0x100
	s_addc_u32 s45, s45, 0
	s_add_u32 s43, s43, 0x100
	s_addc_u32 s83, s83, 0
	s_cmp_gt_u32 s84, 13
	s_cbranch_scc0 .LBB0_177
	s_and_b64 vcc, exec, s[18:19]
	s_cbranch_vccz .LBB0_180
	s_barrier

.LBB0_497:
	s_waitcnt lgkmcnt(0)
	ds_read_b128 v[0:3], v147
	ds_read_b128 v[4:7], v147 offset:1024
	ds_read_b128 v[8:11], v147 offset:2048
	ds_read_b128 v[12:15], v147 offset:3072
	ds_read_b128 v[16:19], v148
	ds_read_b128 v[20:23], v148 offset:1024
	ds_read_b128 v[24:27], v148 offset:2048
	ds_read_b128 v[28:31], v148 offset:3072
	s_ashr_i32 s49, s48, 31
	s_lshl_b64 s[50:51], s[48:49], 17
	s_add_u32 s50, s68, s50
	s_addc_u32 s51, s69, s51
	s_and_b64 s[52:53], s[8:9], exec
	s_cselect_b32 s65, s51, s59
	s_cselect_b32 s64, s50, s58
	s_ashr_i32 s45, s44, 31
	s_lshl_b64 s[52:53], s[44:45], 17
	s_add_u32 s52, s72, s52
	s_addc_u32 s53, s73, s53
	s_and_b64 s[62:63], s[8:9], exec
	s_cselect_b32 s63, s53, s61
	s_cselect_b32 s62, s52, s60
	s_add_u32 s92, s58, 0x10080
	s_addc_u32 s93, s59, 0
	s_add_i32 s94, s81, 0xc000
	v_lshl_add_u64 v[64:65], s[92:93], 0, v[128:129]
	s_mov_b32 m0, s94
	s_add_i32 s45, s81, 0xe000
	ds_read_b128 v[32:35], v149
	ds_read_b128 v[36:39], v149 offset:1024
	ds_read_b128 v[40:43], v149 offset:2048
	ds_read_b128 v[44:47], v149 offset:3072
	ds_read_b128 v[48:51], v149 offset:4096
	ds_read_b128 v[52:55], v149 offset:5120
	ds_read_b128 v[56:59], v149 offset:6144
	ds_read_b128 v[60:63], v149 offset:7168
	global_load_lds_dwordx4 v[64:65], off
	s_mov_b32 m0, s45
	v_lshl_add_u64 v[64:65], s[92:93], 0, v[132:133]
	global_load_lds_dwordx4 v[64:65], off
	s_waitcnt vmcnt(8)
	s_waitcnt lgkmcnt(0)
	s_barrier
	s_waitcnt lgkmcnt(0)
	s_nop 3
	v_mfma_f32_16x16x32_bf16 v[64:67], v[0:3], v[32:35], 0
	v_mfma_f32_16x16x32_bf16 v[68:71], v[8:11], v[32:35], 0
	v_mfma_f32_16x16x32_bf16 v[72:75], v[0:3], v[40:43], 0
	v_mfma_f32_16x16x32_bf16 v[76:79], v[8:11], v[40:43], 0
	v_mfma_f32_16x16x32_bf16 v[80:83], v[0:3], v[48:51], 0
	v_mfma_f32_16x16x32_bf16 v[84:87], v[8:11], v[48:51], 0
	v_mfma_f32_16x16x32_bf16 v[88:91], v[0:3], v[56:59], 0
	v_mfma_f32_16x16x32_bf16 v[92:95], v[8:11], v[56:59], 0
	v_mfma_f32_16x16x32_bf16 v[64:67], v[4:7], v[36:39], v[64:67]
	v_mfma_f32_16x16x32_bf16 v[68:71], v[12:15], v[36:39], v[68:71]
	v_mfma_f32_16x16x32_bf16 v[72:75], v[4:7], v[44:47], v[72:75]
	v_mfma_f32_16x16x32_bf16 v[76:79], v[12:15], v[44:47], v[76:79]
	v_mfma_f32_16x16x32_bf16 v[80:83], v[4:7], v[52:55], v[80:83]
	v_mfma_f32_16x16x32_bf16 v[84:87], v[12:15], v[52:55], v[84:87]
	v_mfma_f32_16x16x32_bf16 v[88:91], v[4:7], v[60:63], v[88:91]
	v_mfma_f32_16x16x32_bf16 v[92:95], v[12:15], v[60:63], v[92:95]
	v_mfma_f32_16x16x32_bf16 v[96:99], v[16:19], v[32:35], 0
	v_mfma_f32_16x16x32_bf16 v[32:35], v[24:27], v[32:35], 0
	v_mfma_f32_16x16x32_bf16 v[96:99], v[20:23], v[36:39], v[96:99]
	v_mfma_f32_16x16x32_bf16 v[32:35], v[28:31], v[36:39], v[32:35]
	v_mfma_f32_16x16x32_bf16 v[36:39], v[16:19], v[40:43], 0
	v_mfma_f32_16x16x32_bf16 v[40:43], v[24:27], v[40:43], 0
	v_mfma_f32_16x16x32_bf16 v[36:39], v[20:23], v[44:47], v[36:39]
	v_mfma_f32_16x16x32_bf16 v[40:43], v[28:31], v[44:47], v[40:43]
	v_mfma_f32_16x16x32_bf16 v[44:47], v[16:19], v[48:51], 0
	v_mfma_f32_16x16x32_bf16 v[48:51], v[24:27], v[48:51], 0
	v_mfma_f32_16x16x32_bf16 v[44:47], v[20:23], v[52:55], v[44:47]
	v_mfma_f32_16x16x32_bf16 v[48:51], v[28:31], v[52:55], v[48:51]
	v_mfma_f32_16x16x32_bf16 v[52:55], v[16:19], v[56:59], 0
	v_mfma_f32_16x16x32_bf16 v[56:59], v[24:27], v[56:59], 0
	v_mfma_f32_16x16x32_bf16 v[52:55], v[20:23], v[60:63], v[52:55]
	v_mfma_f32_16x16x32_bf16 v[56:59], v[28:31], v[60:63], v[56:59]
	s_barrier
	s_add_i32 s92, s88, s80
	v_lshl_add_u64 v[212:213], s[60:61], 0, v[130:131]
	s_add_i32 s49, s92, 0x2000
	v_lshl_add_u64 v[140:141], v[212:213], 0, s[38:39]
	s_mov_b32 m0, s92
	v_lshl_add_u64 v[214:215], s[60:61], 0, v[134:135]
	s_add_u32 s96, s60, 0x10100
	ds_read_b128 v[60:63], v149 offset:16384
	ds_read_b128 v[100:103], v149 offset:17408
	ds_read_b128 v[104:107], v149 offset:18432
	ds_read_b128 v[108:111], v149 offset:19456
	ds_read_b128 v[112:115], v149 offset:20480
	ds_read_b128 v[116:119], v149 offset:21504
	ds_read_b128 v[120:123], v149 offset:22528
	ds_read_b128 v[124:127], v149 offset:23552
	global_load_lds_dwordx4 v[140:141], off
	v_lshl_add_u64 v[140:141], v[214:215], 0, s[38:39]
	s_mov_b32 m0, s49
	s_addc_u32 s97, s61, 0
	s_add_i32 s55, s89, s80
	global_load_lds_dwordx4 v[140:141], off
	v_lshl_add_u64 v[140:141], s[96:97], 0, v[130:131]
	s_mov_b32 m0, s55
	s_add_i32 s57, s55, 0x2000
	global_load_lds_dwordx4 v[140:141], off
	v_lshl_add_u64 v[140:141], s[96:97], 0, v[134:135]
	s_mov_b32 m0, s57
	v_lshl_add_u64 v[216:217], s[58:59], 0, v[128:129]
	global_load_lds_dwordx4 v[140:141], off
	v_lshl_add_u64 v[140:141], v[216:217], 0, s[38:39]
	s_mov_b32 m0, s81
	v_lshl_add_u64 v[218:219], s[58:59], 0, v[132:133]
	global_load_lds_dwordx4 v[140:141], off
	s_mov_b32 m0, s82
	v_lshl_add_u64 v[140:141], v[218:219], 0, s[38:39]
	global_load_lds_dwordx4 v[140:141], off
	s_waitcnt vmcnt(8)
	s_waitcnt lgkmcnt(0)
	s_barrier
	s_waitcnt lgkmcnt(0)
	s_nop 3
	v_mfma_f32_16x16x32_bf16 v[140:143], v[0:3], v[60:63], 0
	v_mfma_f32_16x16x32_bf16 v[156:159], v[0:3], v[104:107], 0
	v_mfma_f32_16x16x32_bf16 v[164:167], v[0:3], v[112:115], 0
	v_mfma_f32_16x16x32_bf16 v[0:3], v[0:3], v[120:123], 0
	v_mfma_f32_16x16x32_bf16 v[140:143], v[4:7], v[100:103], v[140:143]
	v_mfma_f32_16x16x32_bf16 v[156:159], v[4:7], v[108:111], v[156:159]
	v_mfma_f32_16x16x32_bf16 v[164:167], v[4:7], v[116:119], v[164:167]
	v_mfma_f32_16x16x32_bf16 v[0:3], v[4:7], v[124:127], v[0:3]
	v_mfma_f32_16x16x32_bf16 v[4:7], v[8:11], v[120:123], 0
	v_mfma_f32_16x16x32_bf16 v[152:155], v[8:11], v[60:63], 0
	v_mfma_f32_16x16x32_bf16 v[160:163], v[8:11], v[104:107], 0
	v_mfma_f32_16x16x32_bf16 v[168:171], v[8:11], v[112:115], 0
	v_mfma_f32_16x16x32_bf16 v[4:7], v[12:15], v[124:127], v[4:7]
	v_mfma_f32_16x16x32_bf16 v[152:155], v[12:15], v[100:103], v[152:155]
	v_mfma_f32_16x16x32_bf16 v[160:163], v[12:15], v[108:111], v[160:163]
	v_mfma_f32_16x16x32_bf16 v[168:171], v[12:15], v[116:119], v[168:171]
	v_mfma_f32_16x16x32_bf16 v[8:11], v[16:19], v[60:63], 0
	v_mfma_f32_16x16x32_bf16 v[12:15], v[24:27], v[60:63], 0
	v_mfma_f32_16x16x32_bf16 v[8:11], v[20:23], v[100:103], v[8:11]
	v_mfma_f32_16x16x32_bf16 v[12:15], v[28:31], v[100:103], v[12:15]
	v_mfma_f32_16x16x32_bf16 v[60:63], v[16:19], v[104:107], 0
	v_mfma_f32_16x16x32_bf16 v[100:103], v[24:27], v[104:107], 0
	v_mfma_f32_16x16x32_bf16 v[104:107], v[16:19], v[112:115], 0
	v_mfma_f32_16x16x32_bf16 v[16:19], v[16:19], v[120:123], 0
	v_mfma_f32_16x16x32_bf16 v[60:63], v[20:23], v[108:111], v[60:63]
	v_mfma_f32_16x16x32_bf16 v[100:103], v[28:31], v[108:111], v[100:103]
	v_mfma_f32_16x16x32_bf16 v[104:107], v[20:23], v[116:119], v[104:107]
	v_mfma_f32_16x16x32_bf16 v[108:111], v[24:27], v[112:115], 0
	v_mfma_f32_16x16x32_bf16 v[16:19], v[20:23], v[124:127], v[16:19]
	v_mfma_f32_16x16x32_bf16 v[20:23], v[24:27], v[120:123], 0
	v_mfma_f32_16x16x32_bf16 v[108:111], v[28:31], v[116:119], v[108:111]
	v_mfma_f32_16x16x32_bf16 v[20:23], v[28:31], v[124:127], v[20:23]
	s_barrier
	s_add_i32 s95, 0, 0x18000
	s_add_i32 vcc_lo, 0, 0x1c000
	v_add_u32_e32 v151, s95, v145
	v_add_u32_e32 v224, vcc_lo, v145
	ds_read_b128 v[24:27], v151
	ds_read_b128 v[28:31], v151 offset:1024
	ds_read_b128 v[112:115], v151 offset:2048
	ds_read_b128 v[116:119], v151 offset:3072
	ds_read_b128 v[120:123], v224
	ds_read_b128 v[124:127], v224 offset:1024
	ds_read_b128 v[172:175], v224 offset:2048
	ds_read_b128 v[176:179], v224 offset:3072
	s_add_u32 s96, s58, 0x10100
	s_addc_u32 s97, s59, 0
	s_mov_b32 m0, s83
	v_lshl_add_u64 v[220:221], s[96:97], 0, v[128:129]
	ds_read_b128 v[180:183], v149 offset:32768
	ds_read_b128 v[184:187], v149 offset:33792
	ds_read_b128 v[188:191], v149 offset:34816
	ds_read_b128 v[192:195], v149 offset:35840
	ds_read_b128 v[196:199], v149 offset:36864
	ds_read_b128 v[200:203], v149 offset:37888
	ds_read_b128 v[204:207], v149 offset:38912
	ds_read_b128 v[208:211], v149 offset:39936
	global_load_lds_dwordx4 v[220:221], off
	s_mov_b32 m0, s84
	v_lshl_add_u64 v[220:221], s[96:97], 0, v[132:133]
	global_load_lds_dwordx4 v[220:221], off
	s_waitcnt vmcnt(8)
	s_waitcnt lgkmcnt(0)
	s_barrier
	s_waitcnt lgkmcnt(0)
	s_nop 3
	v_mfma_f32_16x16x32_bf16 v[64:67], v[24:27], v[180:183], v[64:67]
	v_mfma_f32_16x16x32_bf16 v[68:71], v[112:115], v[180:183], v[68:71]
	v_mfma_f32_16x16x32_bf16 v[72:75], v[24:27], v[188:191], v[72:75]
	v_mfma_f32_16x16x32_bf16 v[76:79], v[112:115], v[188:191], v[76:79]
	v_mfma_f32_16x16x32_bf16 v[80:83], v[24:27], v[196:199], v[80:83]
	v_mfma_f32_16x16x32_bf16 v[84:87], v[112:115], v[196:199], v[84:87]
	v_mfma_f32_16x16x32_bf16 v[88:91], v[24:27], v[204:207], v[88:91]
	v_mfma_f32_16x16x32_bf16 v[92:95], v[112:115], v[204:207], v[92:95]
	v_mfma_f32_16x16x32_bf16 v[64:67], v[28:31], v[184:187], v[64:67]
	v_mfma_f32_16x16x32_bf16 v[68:71], v[116:119], v[184:187], v[68:71]
	v_mfma_f32_16x16x32_bf16 v[72:75], v[28:31], v[192:195], v[72:75]
	v_mfma_f32_16x16x32_bf16 v[76:79], v[116:119], v[192:195], v[76:79]
	v_mfma_f32_16x16x32_bf16 v[80:83], v[28:31], v[200:203], v[80:83]
	v_mfma_f32_16x16x32_bf16 v[84:87], v[116:119], v[200:203], v[84:87]
	v_mfma_f32_16x16x32_bf16 v[88:91], v[28:31], v[208:211], v[88:91]
	v_mfma_f32_16x16x32_bf16 v[92:95], v[116:119], v[208:211], v[92:95]
	v_mfma_f32_16x16x32_bf16 v[96:99], v[120:123], v[180:183], v[96:99]
	v_mfma_f32_16x16x32_bf16 v[32:35], v[172:175], v[180:183], v[32:35]
	v_mfma_f32_16x16x32_bf16 v[36:39], v[120:123], v[188:191], v[36:39]
	v_mfma_f32_16x16x32_bf16 v[40:43], v[172:175], v[188:191], v[40:43]
	v_mfma_f32_16x16x32_bf16 v[44:47], v[120:123], v[196:199], v[44:47]
	v_mfma_f32_16x16x32_bf16 v[48:51], v[172:175], v[196:199], v[48:51]
	v_mfma_f32_16x16x32_bf16 v[52:55], v[120:123], v[204:207], v[52:55]
	v_mfma_f32_16x16x32_bf16 v[56:59], v[172:175], v[204:207], v[56:59]
	v_mfma_f32_16x16x32_bf16 v[96:99], v[124:127], v[184:187], v[96:99]
	v_mfma_f32_16x16x32_bf16 v[32:35], v[176:179], v[184:187], v[32:35]
	v_mfma_f32_16x16x32_bf16 v[36:39], v[124:127], v[192:195], v[36:39]
	v_mfma_f32_16x16x32_bf16 v[40:43], v[176:179], v[192:195], v[40:43]
	v_mfma_f32_16x16x32_bf16 v[44:47], v[124:127], v[200:203], v[44:47]
	v_mfma_f32_16x16x32_bf16 v[48:51], v[176:179], v[200:203], v[48:51]
	v_mfma_f32_16x16x32_bf16 v[52:55], v[124:127], v[208:211], v[52:55]
	v_mfma_f32_16x16x32_bf16 v[56:59], v[176:179], v[208:211], v[56:59]
	s_barrier
	s_add_i32 s95, s95, s80
	s_add_i32 s93, s95, 0x2000
	v_lshl_add_u64 v[212:213], v[212:213], 0, s[40:41]
	s_mov_b32 m0, s95
	s_add_u32 s96, s60, 0x10180
	ds_read_b128 v[180:183], v149 offset:49152
	ds_read_b128 v[184:187], v149 offset:50176
	ds_read_b128 v[188:191], v149 offset:51200
	ds_read_b128 v[192:195], v149 offset:52224
	ds_read_b128 v[196:199], v149 offset:53248
	ds_read_b128 v[200:203], v149 offset:54272
	ds_read_b128 v[204:207], v149 offset:55296
	ds_read_b128 v[208:211], v149 offset:56320
	global_load_lds_dwordx4 v[212:213], off
	v_lshl_add_u64 v[212:213], v[214:215], 0, s[40:41]
	s_mov_b32 m0, s93
	s_addc_u32 s97, s61, 0
	s_add_i32 s60, vcc_lo, s80
	global_load_lds_dwordx4 v[212:213], off
	v_lshl_add_u64 v[212:213], s[96:97], 0, v[130:131]
	s_mov_b32 m0, s60
	s_add_i32 s61, s60, 0x2000
	global_load_lds_dwordx4 v[212:213], off
	s_mov_b32 m0, s61
	v_lshl_add_u64 v[212:213], s[96:97], 0, v[134:135]
	global_load_lds_dwordx4 v[212:213], off
	s_mov_b32 m0, s86
	v_lshl_add_u64 v[212:213], v[216:217], 0, s[40:41]
	global_load_lds_dwordx4 v[212:213], off
	s_mov_b32 m0, s87
	v_lshl_add_u64 v[212:213], v[218:219], 0, s[40:41]
	global_load_lds_dwordx4 v[212:213], off
	s_waitcnt vmcnt(8)
	s_waitcnt lgkmcnt(0)
	s_barrier
	s_waitcnt lgkmcnt(0)
	s_nop 3
	v_mfma_f32_16x16x32_bf16 v[0:3], v[24:27], v[204:207], v[0:3]
	v_mfma_f32_16x16x32_bf16 v[4:7], v[112:115], v[204:207], v[4:7]
	v_mfma_f32_16x16x32_bf16 v[140:143], v[24:27], v[180:183], v[140:143]
	v_mfma_f32_16x16x32_bf16 v[152:155], v[112:115], v[180:183], v[152:155]
	v_mfma_f32_16x16x32_bf16 v[156:159], v[24:27], v[188:191], v[156:159]
	v_mfma_f32_16x16x32_bf16 v[160:163], v[112:115], v[188:191], v[160:163]
	v_mfma_f32_16x16x32_bf16 v[164:167], v[24:27], v[196:199], v[164:167]
	v_mfma_f32_16x16x32_bf16 v[168:171], v[112:115], v[196:199], v[168:171]
	v_mfma_f32_16x16x32_bf16 v[0:3], v[28:31], v[208:211], v[0:3]
	v_mfma_f32_16x16x32_bf16 v[4:7], v[116:119], v[208:211], v[4:7]
	v_mfma_f32_16x16x32_bf16 v[140:143], v[28:31], v[184:187], v[140:143]
	v_mfma_f32_16x16x32_bf16 v[152:155], v[116:119], v[184:187], v[152:155]
	v_mfma_f32_16x16x32_bf16 v[156:159], v[28:31], v[192:195], v[156:159]
	v_mfma_f32_16x16x32_bf16 v[160:163], v[116:119], v[192:195], v[160:163]
	v_mfma_f32_16x16x32_bf16 v[164:167], v[28:31], v[200:203], v[164:167]
	v_mfma_f32_16x16x32_bf16 v[168:171], v[116:119], v[200:203], v[168:171]
	v_mfma_f32_16x16x32_bf16 v[8:11], v[120:123], v[180:183], v[8:11]
	v_mfma_f32_16x16x32_bf16 v[12:15], v[172:175], v[180:183], v[12:15]
	v_mfma_f32_16x16x32_bf16 v[24:27], v[120:123], v[188:191], v[60:63]
	v_mfma_f32_16x16x32_bf16 v[28:31], v[172:175], v[188:191], v[100:103]
	v_mfma_f32_16x16x32_bf16 v[60:63], v[120:123], v[196:199], v[104:107]
	v_mfma_f32_16x16x32_bf16 v[100:103], v[172:175], v[196:199], v[108:111]
	v_mfma_f32_16x16x32_bf16 v[16:19], v[120:123], v[204:207], v[16:19]
	v_mfma_f32_16x16x32_bf16 v[20:23], v[172:175], v[204:207], v[20:23]
	v_mfma_f32_16x16x32_bf16 v[8:11], v[124:127], v[184:187], v[8:11]
	v_mfma_f32_16x16x32_bf16 v[12:15], v[176:179], v[184:187], v[12:15]
	v_mfma_f32_16x16x32_bf16 v[24:27], v[124:127], v[192:195], v[24:27]
	v_mfma_f32_16x16x32_bf16 v[28:31], v[176:179], v[192:195], v[28:31]
	v_mfma_f32_16x16x32_bf16 v[60:63], v[124:127], v[200:203], v[60:63]
	v_mfma_f32_16x16x32_bf16 v[100:103], v[176:179], v[200:203], v[100:103]
	v_mfma_f32_16x16x32_bf16 v[16:19], v[124:127], v[208:211], v[16:19]
	v_mfma_f32_16x16x32_bf16 v[20:23], v[176:179], v[208:211], v[20:23]
	s_barrier
	ds_read_b128 v[104:107], v147
	ds_read_b128 v[108:111], v147 offset:1024
	ds_read_b128 v[112:115], v147 offset:2048
	ds_read_b128 v[116:119], v147 offset:3072
	ds_read_b128 v[120:123], v148
	ds_read_b128 v[124:127], v148 offset:1024
	ds_read_b128 v[172:175], v148 offset:2048
	ds_read_b128 v[176:179], v148 offset:3072
	s_add_u32 s58, s58, 0x10180
	s_addc_u32 s59, s59, 0
	s_mov_b32 m0, s94
	v_lshl_add_u64 v[212:213], s[58:59], 0, v[128:129]
	ds_read_b128 v[180:183], v149
	ds_read_b128 v[184:187], v149 offset:1024
	ds_read_b128 v[188:191], v149 offset:2048
	ds_read_b128 v[192:195], v149 offset:3072
	ds_read_b128 v[196:199], v149 offset:4096
	ds_read_b128 v[200:203], v149 offset:5120
	ds_read_b128 v[204:207], v149 offset:6144
	ds_read_b128 v[208:211], v149 offset:7168
	global_load_lds_dwordx4 v[212:213], off
	s_mov_b32 m0, s45
	v_lshl_add_u64 v[212:213], s[58:59], 0, v[132:133]
	global_load_lds_dwordx4 v[212:213], off
	s_waitcnt vmcnt(8)
	s_waitcnt lgkmcnt(0)
	s_barrier
	s_waitcnt lgkmcnt(0)
	s_nop 3
	v_mfma_f32_16x16x32_bf16 v[64:67], v[104:107], v[180:183], v[64:67]
	v_mfma_f32_16x16x32_bf16 v[68:71], v[112:115], v[180:183], v[68:71]
	v_mfma_f32_16x16x32_bf16 v[72:75], v[104:107], v[188:191], v[72:75]
	v_mfma_f32_16x16x32_bf16 v[76:79], v[112:115], v[188:191], v[76:79]
	v_mfma_f32_16x16x32_bf16 v[80:83], v[104:107], v[196:199], v[80:83]
	v_mfma_f32_16x16x32_bf16 v[84:87], v[112:115], v[196:199], v[84:87]
	v_mfma_f32_16x16x32_bf16 v[88:91], v[104:107], v[204:207], v[88:91]
	v_mfma_f32_16x16x32_bf16 v[64:67], v[108:111], v[184:187], v[64:67]
	v_mfma_f32_16x16x32_bf16 v[68:71], v[116:119], v[184:187], v[68:71]
	v_mfma_f32_16x16x32_bf16 v[72:75], v[108:111], v[192:195], v[72:75]
	v_mfma_f32_16x16x32_bf16 v[76:79], v[116:119], v[192:195], v[76:79]
	v_mfma_f32_16x16x32_bf16 v[80:83], v[108:111], v[200:203], v[80:83]
	v_mfma_f32_16x16x32_bf16 v[84:87], v[116:119], v[200:203], v[84:87]
	v_mfma_f32_16x16x32_bf16 v[212:215], v[108:111], v[208:211], v[88:91]
	v_mfma_f32_16x16x32_bf16 v[88:91], v[112:115], v[204:207], v[92:95]
	v_mfma_f32_16x16x32_bf16 v[216:219], v[116:119], v[208:211], v[88:91]
	v_mfma_f32_16x16x32_bf16 v[88:91], v[120:123], v[180:183], v[96:99]
	v_mfma_f32_16x16x32_bf16 v[32:35], v[172:175], v[180:183], v[32:35]
	v_mfma_f32_16x16x32_bf16 v[36:39], v[120:123], v[188:191], v[36:39]
	v_mfma_f32_16x16x32_bf16 v[40:43], v[172:175], v[188:191], v[40:43]
	v_mfma_f32_16x16x32_bf16 v[44:47], v[120:123], v[196:199], v[44:47]
	v_mfma_f32_16x16x32_bf16 v[48:51], v[172:175], v[196:199], v[48:51]
	v_mfma_f32_16x16x32_bf16 v[52:55], v[120:123], v[204:207], v[52:55]
	v_mfma_f32_16x16x32_bf16 v[56:59], v[172:175], v[204:207], v[56:59]
	v_mfma_f32_16x16x32_bf16 v[96:99], v[124:127], v[184:187], v[88:91]
	v_mfma_f32_16x16x32_bf16 v[32:35], v[176:179], v[184:187], v[32:35]
	v_mfma_f32_16x16x32_bf16 v[36:39], v[124:127], v[192:195], v[36:39]
	v_mfma_f32_16x16x32_bf16 v[40:43], v[176:179], v[192:195], v[40:43]
	v_mfma_f32_16x16x32_bf16 v[44:47], v[124:127], v[200:203], v[44:47]
	v_mfma_f32_16x16x32_bf16 v[48:51], v[176:179], v[200:203], v[48:51]
	v_mfma_f32_16x16x32_bf16 v[52:55], v[124:127], v[208:211], v[52:55]
	v_mfma_f32_16x16x32_bf16 v[56:59], v[176:179], v[208:211], v[56:59]
	s_barrier
	s_mov_b32 m0, s92
	v_lshl_add_u64 v[244:245], s[62:63], 0, v[130:131]
	s_add_u32 s58, s62, 0x10000
	ds_read_b128 v[88:91], v149 offset:16384
	ds_read_b128 v[92:95], v149 offset:17408
	ds_read_b128 v[180:183], v149 offset:18432
	ds_read_b128 v[184:187], v149 offset:19456
	ds_read_b128 v[188:191], v149 offset:20480
	ds_read_b128 v[192:195], v149 offset:21504
	ds_read_b128 v[196:199], v149 offset:22528
	ds_read_b128 v[200:203], v149 offset:23552
	global_load_lds_dwordx4 v[244:245], off
	v_lshl_add_u64 v[246:247], s[62:63], 0, v[134:135]
	s_mov_b32 m0, s49
	s_addc_u32 s59, s63, 0
	global_load_lds_dwordx4 v[246:247], off
	v_lshl_add_u64 v[204:205], s[58:59], 0, v[130:131]
	s_mov_b32 m0, s55
	v_lshl_add_u64 v[248:249], s[64:65], 0, v[128:129]
	global_load_lds_dwordx4 v[204:205], off
	v_lshl_add_u64 v[204:205], s[58:59], 0, v[134:135]
	s_mov_b32 m0, s57
	v_lshl_add_u64 v[250:251], s[64:65], 0, v[132:133]
	global_load_lds_dwordx4 v[204:205], off
	s_mov_b32 m0, s81
	s_nop 0
	global_load_lds_dwordx4 v[248:249], off
	s_mov_b32 m0, s82
	s_nop 0
	global_load_lds_dwordx4 v[250:251], off
	s_waitcnt vmcnt(8)
	s_waitcnt lgkmcnt(0)
	s_barrier
	s_waitcnt lgkmcnt(0)
	s_nop 3
	v_mfma_f32_16x16x32_bf16 v[0:3], v[104:107], v[196:199], v[0:3]
	v_mfma_f32_16x16x32_bf16 v[4:7], v[112:115], v[196:199], v[4:7]
	v_mfma_f32_16x16x32_bf16 v[140:143], v[104:107], v[88:91], v[140:143]
	v_mfma_f32_16x16x32_bf16 v[152:155], v[112:115], v[88:91], v[152:155]
	v_mfma_f32_16x16x32_bf16 v[156:159], v[104:107], v[180:183], v[156:159]
	v_mfma_f32_16x16x32_bf16 v[160:163], v[112:115], v[180:183], v[160:163]
	v_mfma_f32_16x16x32_bf16 v[164:167], v[104:107], v[188:191], v[164:167]
	v_mfma_f32_16x16x32_bf16 v[168:171], v[112:115], v[188:191], v[168:171]
	v_mfma_f32_16x16x32_bf16 v[0:3], v[108:111], v[200:203], v[0:3]
	v_mfma_f32_16x16x32_bf16 v[4:7], v[116:119], v[200:203], v[4:7]
	v_mfma_f32_16x16x32_bf16 v[140:143], v[108:111], v[92:95], v[140:143]
	v_mfma_f32_16x16x32_bf16 v[152:155], v[116:119], v[92:95], v[152:155]
	v_mfma_f32_16x16x32_bf16 v[156:159], v[108:111], v[184:187], v[156:159]
	v_mfma_f32_16x16x32_bf16 v[160:163], v[116:119], v[184:187], v[160:163]
	v_mfma_f32_16x16x32_bf16 v[164:167], v[108:111], v[192:195], v[164:167]
	v_mfma_f32_16x16x32_bf16 v[168:171], v[116:119], v[192:195], v[168:171]
	v_mfma_f32_16x16x32_bf16 v[8:11], v[120:123], v[88:91], v[8:11]
	v_mfma_f32_16x16x32_bf16 v[204:207], v[124:127], v[92:95], v[8:11]
	v_mfma_f32_16x16x32_bf16 v[8:11], v[172:175], v[88:91], v[12:15]
	v_mfma_f32_16x16x32_bf16 v[208:211], v[176:179], v[92:95], v[8:11]
	v_mfma_f32_16x16x32_bf16 v[8:11], v[120:123], v[180:183], v[24:27]
	v_mfma_f32_16x16x32_bf16 v[220:223], v[124:127], v[184:187], v[8:11]
	v_mfma_f32_16x16x32_bf16 v[8:11], v[172:175], v[180:183], v[28:31]
	v_mfma_f32_16x16x32_bf16 v[180:183], v[176:179], v[184:187], v[8:11]
	v_mfma_f32_16x16x32_bf16 v[8:11], v[120:123], v[188:191], v[60:63]
	v_mfma_f32_16x16x32_bf16 v[184:187], v[124:127], v[192:195], v[8:11]
	v_mfma_f32_16x16x32_bf16 v[8:11], v[172:175], v[188:191], v[100:103]
	v_mfma_f32_16x16x32_bf16 v[188:191], v[176:179], v[192:195], v[8:11]
	v_mfma_f32_16x16x32_bf16 v[8:11], v[120:123], v[196:199], v[16:19]
	v_mfma_f32_16x16x32_bf16 v[192:195], v[124:127], v[200:203], v[8:11]
	v_mfma_f32_16x16x32_bf16 v[8:11], v[172:175], v[196:199], v[20:23]
	v_mfma_f32_16x16x32_bf16 v[172:175], v[176:179], v[200:203], v[8:11]
	s_barrier
	s_nop 4
	ds_read_b128 v[8:11], v151
	ds_read_b128 v[12:15], v151 offset:1024
	ds_read_b128 v[16:19], v151 offset:2048
	ds_read_b128 v[20:23], v151 offset:3072
	ds_read_b128 v[176:179], v224
	ds_read_b128 v[196:199], v224 offset:1024
	ds_read_b128 v[200:203], v224 offset:2048
	ds_read_b128 v[224:227], v224 offset:3072
	s_add_u32 s58, s64, 0x10000
	s_addc_u32 s59, s65, 0
	s_mov_b32 m0, s83
	v_lshl_add_u64 v[88:89], s[58:59], 0, v[128:129]
	ds_read_b128 v[24:27], v149 offset:32768
	ds_read_b128 v[28:31], v149 offset:33792
	ds_read_b128 v[60:63], v149 offset:34816
	ds_read_b128 v[100:103], v149 offset:35840
	ds_read_b128 v[228:231], v149 offset:36864
	ds_read_b128 v[232:235], v149 offset:37888
	ds_read_b128 v[236:239], v149 offset:38912
	ds_read_b128 v[240:243], v149 offset:39936
	global_load_lds_dwordx4 v[88:89], off
	s_mov_b32 m0, s84
	v_lshl_add_u64 v[88:89], s[58:59], 0, v[132:133]
	global_load_lds_dwordx4 v[88:89], off
	s_waitcnt vmcnt(8)
	s_waitcnt lgkmcnt(0)
	s_barrier
	s_waitcnt lgkmcnt(0)
	s_nop 3
	v_mfma_f32_16x16x32_bf16 v[64:67], v[8:11], v[24:27], v[64:67]
	v_mfma_f32_16x16x32_bf16 v[120:123], v[12:15], v[28:31], v[64:67]
	v_mfma_f32_16x16x32_bf16 v[64:67], v[16:19], v[24:27], v[68:71]
	v_mfma_f32_16x16x32_bf16 v[124:127], v[20:23], v[28:31], v[64:67]
	v_mfma_f32_16x16x32_bf16 v[64:67], v[8:11], v[60:63], v[72:75]
	v_mfma_f32_16x16x32_bf16 v[104:107], v[12:15], v[100:103], v[64:67]
	v_mfma_f32_16x16x32_bf16 v[64:67], v[16:19], v[60:63], v[76:79]
	v_mfma_f32_16x16x32_bf16 v[108:111], v[20:23], v[100:103], v[64:67]
	v_mfma_f32_16x16x32_bf16 v[64:67], v[8:11], v[228:231], v[80:83]
	v_mfma_f32_16x16x32_bf16 v[88:91], v[12:15], v[232:235], v[64:67]
	v_mfma_f32_16x16x32_bf16 v[64:67], v[16:19], v[228:231], v[84:87]
	v_mfma_f32_16x16x32_bf16 v[92:95], v[20:23], v[232:235], v[64:67]
	v_mfma_f32_16x16x32_bf16 v[64:67], v[8:11], v[236:239], v[212:215]
	v_mfma_f32_16x16x32_bf16 v[72:75], v[12:15], v[240:243], v[64:67]
	v_mfma_f32_16x16x32_bf16 v[64:67], v[16:19], v[236:239], v[216:219]
	v_mfma_f32_16x16x32_bf16 v[76:79], v[20:23], v[240:243], v[64:67]
	v_mfma_f32_16x16x32_bf16 v[64:67], v[176:179], v[24:27], v[96:99]
	v_mfma_f32_16x16x32_bf16 v[24:27], v[200:203], v[24:27], v[32:35]
	v_mfma_f32_16x16x32_bf16 v[116:119], v[224:227], v[28:31], v[24:27]
	v_mfma_f32_16x16x32_bf16 v[24:27], v[176:179], v[60:63], v[36:39]
	v_mfma_f32_16x16x32_bf16 v[96:99], v[196:199], v[100:103], v[24:27]
	v_mfma_f32_16x16x32_bf16 v[24:27], v[200:203], v[60:63], v[40:43]
	v_mfma_f32_16x16x32_bf16 v[100:103], v[224:227], v[100:103], v[24:27]
	v_mfma_f32_16x16x32_bf16 v[24:27], v[176:179], v[228:231], v[44:47]
	v_mfma_f32_16x16x32_bf16 v[80:83], v[196:199], v[232:235], v[24:27]
	v_mfma_f32_16x16x32_bf16 v[24:27], v[200:203], v[228:231], v[48:51]
	v_mfma_f32_16x16x32_bf16 v[84:87], v[224:227], v[232:235], v[24:27]
	v_mfma_f32_16x16x32_bf16 v[24:27], v[176:179], v[236:239], v[52:55]
	v_mfma_f32_16x16x32_bf16 v[112:115], v[196:199], v[28:31], v[64:67]
	v_mfma_f32_16x16x32_bf16 v[64:67], v[196:199], v[240:243], v[24:27]
	v_mfma_f32_16x16x32_bf16 v[24:27], v[200:203], v[236:239], v[56:59]
	v_mfma_f32_16x16x32_bf16 v[68:71], v[224:227], v[240:243], v[24:27]
	s_barrier
	s_mov_b32 m0, s95
	s_nop 3
	v_lshl_add_u64 v[24:25], v[244:245], 0, s[18:19]
	s_add_u32 s58, s62, 0x10080
	ds_read_b128 v[32:35], v149 offset:49152
	ds_read_b128 v[36:39], v149 offset:50176
	ds_read_b128 v[212:215], v149 offset:51200
	ds_read_b128 v[216:219], v149 offset:52224
	ds_read_b128 v[228:231], v149 offset:53248
	ds_read_b128 v[232:235], v149 offset:54272
	ds_read_b128 v[236:239], v149 offset:55296
	ds_read_b128 v[240:243], v149 offset:56320
	global_load_lds_dwordx4 v[24:25], off
	v_lshl_add_u64 v[24:25], v[246:247], 0, s[18:19]
	s_mov_b32 m0, s93
	s_addc_u32 s59, s63, 0
	global_load_lds_dwordx4 v[24:25], off
	s_mov_b32 m0, s60
	v_lshl_add_u64 v[24:25], s[58:59], 0, v[130:131]
	global_load_lds_dwordx4 v[24:25], off
	s_mov_b32 m0, s61
	v_lshl_add_u64 v[24:25], s[58:59], 0, v[134:135]
	global_load_lds_dwordx4 v[24:25], off
	s_mov_b32 m0, s86
	v_lshl_add_u64 v[24:25], v[248:249], 0, s[18:19]
	global_load_lds_dwordx4 v[24:25], off
	s_mov_b32 m0, s87
	v_lshl_add_u64 v[24:25], v[250:251], 0, s[18:19]
	global_load_lds_dwordx4 v[24:25], off
	s_waitcnt vmcnt(8)
	s_waitcnt lgkmcnt(0)
	s_barrier
	s_waitcnt lgkmcnt(0)
	s_nop 3
	v_mfma_f32_16x16x32_bf16 v[24:27], v[8:11], v[32:35], v[140:143]
	v_mfma_f32_16x16x32_bf16 v[56:59], v[12:15], v[36:39], v[24:27]
	v_mfma_f32_16x16x32_bf16 v[24:27], v[16:19], v[32:35], v[152:155]
	v_mfma_f32_16x16x32_bf16 v[60:63], v[20:23], v[36:39], v[24:27]
	v_mfma_f32_16x16x32_bf16 v[24:27], v[8:11], v[212:215], v[156:159]
	v_mfma_f32_16x16x32_bf16 v[40:43], v[12:15], v[216:219], v[24:27]
	v_mfma_f32_16x16x32_bf16 v[24:27], v[16:19], v[212:215], v[160:163]
	v_mfma_f32_16x16x32_bf16 v[0:3], v[8:11], v[236:239], v[0:3]
	v_mfma_f32_16x16x32_bf16 v[44:47], v[20:23], v[216:219], v[24:27]
	v_mfma_f32_16x16x32_bf16 v[24:27], v[8:11], v[228:231], v[164:167]
	v_mfma_f32_16x16x32_bf16 v[28:31], v[16:19], v[228:231], v[168:171]
	v_mfma_f32_16x16x32_bf16 v[8:11], v[12:15], v[240:243], v[0:3]
	v_mfma_f32_16x16x32_bf16 v[0:3], v[16:19], v[236:239], v[4:7]
	v_mfma_f32_16x16x32_bf16 v[24:27], v[12:15], v[232:235], v[24:27]
	v_mfma_f32_16x16x32_bf16 v[28:31], v[20:23], v[232:235], v[28:31]
	v_mfma_f32_16x16x32_bf16 v[12:15], v[20:23], v[240:243], v[0:3]
	v_mfma_f32_16x16x32_bf16 v[0:3], v[176:179], v[32:35], v[204:207]
	v_mfma_f32_16x16x32_bf16 v[48:51], v[196:199], v[36:39], v[0:3]
	v_mfma_f32_16x16x32_bf16 v[0:3], v[200:203], v[32:35], v[208:211]
	v_mfma_f32_16x16x32_bf16 v[52:55], v[224:227], v[36:39], v[0:3]
	v_mfma_f32_16x16x32_bf16 v[0:3], v[176:179], v[212:215], v[220:223]
	v_mfma_f32_16x16x32_bf16 v[32:35], v[196:199], v[216:219], v[0:3]
	v_mfma_f32_16x16x32_bf16 v[0:3], v[200:203], v[212:215], v[180:183]
	v_mfma_f32_16x16x32_bf16 v[36:39], v[224:227], v[216:219], v[0:3]
	v_mfma_f32_16x16x32_bf16 v[0:3], v[176:179], v[228:231], v[184:187]
	v_mfma_f32_16x16x32_bf16 v[16:19], v[196:199], v[232:235], v[0:3]
	v_mfma_f32_16x16x32_bf16 v[0:3], v[200:203], v[228:231], v[188:191]
	v_mfma_f32_16x16x32_bf16 v[20:23], v[224:227], v[232:235], v[0:3]
	v_mfma_f32_16x16x32_bf16 v[0:3], v[176:179], v[236:239], v[192:195]
	v_mfma_f32_16x16x32_bf16 v[4:7], v[200:203], v[236:239], v[172:175]
	v_mfma_f32_16x16x32_bf16 v[0:3], v[196:199], v[240:243], v[0:3]
	v_mfma_f32_16x16x32_bf16 v[4:7], v[224:227], v[240:243], v[4:7]
	s_barrier
	s_andn2_b64 vcc, exec, s[24:25]
	s_cbranch_vccnz .LBB0_499
	s_barrier

.LBB0_546:
	v_add_u32_e32 v1, s80, v155
	ds_read_b128 v[146:149], v1
	ds_read_b128 v[150:153], v1 offset:1024
	ds_read_b128 v[162:165], v1 offset:2048
	ds_read_b128 v[166:169], v1 offset:3072
	v_add_u32_e32 v1, s81, v155
	ds_read_b128 v[170:173], v1
	ds_read_b128 v[174:177], v1 offset:1024
	ds_read_b128 v[178:181], v1 offset:2048
	ds_read_b128 v[182:185], v1 offset:3072
	s_and_b64 s[56:57], exec, s[56:57]
	s_cselect_b32 s57, s43, s91
	s_cselect_b32 s56, s89, s90
	s_add_u32 s96, s93, 0x40000
	s_addc_u32 s97, s94, 0
	v_lshl_add_u64 v[2:3], s[96:97], 0, v[132:133]
	s_add_i32 m0, s9, 0xc000
	ds_read_b128 v[186:189], v159
	ds_read_b128 v[190:193], v159 offset:1024
	ds_read_b128 v[194:197], v159 offset:2048
	ds_read_b128 v[198:201], v159 offset:3072
	ds_read_b128 v[202:205], v159 offset:4096
	ds_read_b128 v[206:209], v159 offset:5120
	ds_read_b128 v[210:213], v159 offset:6144
	ds_read_b128 v[214:217], v159 offset:7168
	global_load_lds_dwordx4 v[2:3], off
	s_add_i32 m0, s9, 0xe000
	v_lshl_add_u64 v[2:3], s[96:97], 0, v[136:137]
	global_load_lds_dwordx4 v[2:3], off
	s_waitcnt vmcnt(8)
	s_waitcnt lgkmcnt(0)
	s_barrier
	s_waitcnt lgkmcnt(0)
	s_nop 3
	v_mfma_f32_16x16x32_bf16 v[128:131], v[146:149], v[186:189], v[128:131]
	v_mfma_f32_16x16x32_bf16 v[124:127], v[162:165], v[186:189], v[124:127]
	v_mfma_f32_16x16x32_bf16 v[112:115], v[146:149], v[194:197], v[112:115]
	v_mfma_f32_16x16x32_bf16 v[108:111], v[162:165], v[194:197], v[108:111]
	v_mfma_f32_16x16x32_bf16 v[96:99], v[146:149], v[202:205], v[96:99]
	v_mfma_f32_16x16x32_bf16 v[92:95], v[162:165], v[202:205], v[92:95]
	v_mfma_f32_16x16x32_bf16 v[80:83], v[146:149], v[210:213], v[80:83]
	v_mfma_f32_16x16x32_bf16 v[76:79], v[162:165], v[210:213], v[76:79]
	v_mfma_f32_16x16x32_bf16 v[128:131], v[150:153], v[190:193], v[128:131]
	v_mfma_f32_16x16x32_bf16 v[124:127], v[166:169], v[190:193], v[124:127]
	v_mfma_f32_16x16x32_bf16 v[112:115], v[150:153], v[198:201], v[112:115]
	v_mfma_f32_16x16x32_bf16 v[108:111], v[166:169], v[198:201], v[108:111]
	v_mfma_f32_16x16x32_bf16 v[96:99], v[150:153], v[206:209], v[96:99]
	v_mfma_f32_16x16x32_bf16 v[92:95], v[166:169], v[206:209], v[92:95]
	v_mfma_f32_16x16x32_bf16 v[80:83], v[150:153], v[214:217], v[80:83]
	v_mfma_f32_16x16x32_bf16 v[76:79], v[166:169], v[214:217], v[76:79]
	v_mfma_f32_16x16x32_bf16 v[120:123], v[170:173], v[186:189], v[120:123]
	v_mfma_f32_16x16x32_bf16 v[116:119], v[178:181], v[186:189], v[116:119]
	v_mfma_f32_16x16x32_bf16 v[104:107], v[170:173], v[194:197], v[104:107]
	v_mfma_f32_16x16x32_bf16 v[100:103], v[178:181], v[194:197], v[100:103]
	v_mfma_f32_16x16x32_bf16 v[88:91], v[170:173], v[202:205], v[88:91]
	v_mfma_f32_16x16x32_bf16 v[84:87], v[178:181], v[202:205], v[84:87]
	v_mfma_f32_16x16x32_bf16 v[72:75], v[170:173], v[210:213], v[72:75]
	v_mfma_f32_16x16x32_bf16 v[68:71], v[178:181], v[210:213], v[68:71]
	v_mfma_f32_16x16x32_bf16 v[120:123], v[174:177], v[190:193], v[120:123]
	v_mfma_f32_16x16x32_bf16 v[116:119], v[182:185], v[190:193], v[116:119]
	v_mfma_f32_16x16x32_bf16 v[104:107], v[174:177], v[198:201], v[104:107]
	v_mfma_f32_16x16x32_bf16 v[100:103], v[182:185], v[198:201], v[100:103]
	v_mfma_f32_16x16x32_bf16 v[88:91], v[174:177], v[206:209], v[88:91]
	v_mfma_f32_16x16x32_bf16 v[84:87], v[182:185], v[206:209], v[84:87]
	v_mfma_f32_16x16x32_bf16 v[72:75], v[174:177], v[214:217], v[72:75]
	v_mfma_f32_16x16x32_bf16 v[68:71], v[182:185], v[214:217], v[68:71]
	s_barrier
	s_add_i32 s14, s80, s0
	v_lshl_add_u64 v[218:219], s[56:57], 0, v[134:135]
	s_mov_b32 m0, s14
	ds_read_b128 v[186:189], v159 offset:16384
	ds_read_b128 v[190:193], v159 offset:17408
	ds_read_b128 v[194:197], v159 offset:18432
	ds_read_b128 v[198:201], v159 offset:19456
	ds_read_b128 v[202:205], v159 offset:20480
	ds_read_b128 v[206:209], v159 offset:21504
	ds_read_b128 v[210:213], v159 offset:22528
	ds_read_b128 v[214:217], v159 offset:23552
	global_load_lds_dwordx4 v[218:219], off
	s_add_i32 m0, s14, 0x2000
	s_add_u32 s94, s56, 0x80000
	v_lshl_add_u64 v[220:221], s[56:57], 0, v[138:139]
	s_addc_u32 s95, s57, 0
	s_add_i32 s14, s81, s0
	global_load_lds_dwordx4 v[220:221], off
	v_lshl_add_u64 v[2:3], s[94:95], 0, v[134:135]
	s_mov_b32 m0, s14
	v_lshl_add_u64 v[222:223], s[58:59], 0, v[132:133]
	global_load_lds_dwordx4 v[2:3], off
	v_lshl_add_u64 v[2:3], s[94:95], 0, v[138:139]
	s_add_i32 m0, s14, 0x2000
	v_lshl_add_u64 v[224:225], s[58:59], 0, v[136:137]
	global_load_lds_dwordx4 v[2:3], off
	s_mov_b32 m0, s9
	s_nop 0
	global_load_lds_dwordx4 v[222:223], off
	s_mov_b32 m0, s62
	s_nop 0
	global_load_lds_dwordx4 v[224:225], off
	s_waitcnt vmcnt(8)
	s_waitcnt lgkmcnt(0)
	s_barrier
	s_waitcnt lgkmcnt(0)
	s_nop 3
	v_mfma_f32_16x16x32_bf16 v[64:67], v[146:149], v[186:189], v[64:67]
	v_mfma_f32_16x16x32_bf16 v[60:63], v[162:165], v[186:189], v[60:63]
	v_mfma_f32_16x16x32_bf16 v[48:51], v[146:149], v[194:197], v[48:51]
	v_mfma_f32_16x16x32_bf16 v[44:47], v[162:165], v[194:197], v[44:47]
	v_mfma_f32_16x16x32_bf16 v[32:35], v[146:149], v[202:205], v[32:35]
	v_mfma_f32_16x16x32_bf16 v[28:31], v[162:165], v[202:205], v[28:31]
	v_mfma_f32_16x16x32_bf16 v[16:19], v[146:149], v[210:213], v[16:19]
	v_mfma_f32_16x16x32_bf16 v[12:15], v[162:165], v[210:213], v[12:15]
	v_mfma_f32_16x16x32_bf16 v[64:67], v[150:153], v[190:193], v[64:67]
	v_mfma_f32_16x16x32_bf16 v[60:63], v[166:169], v[190:193], v[60:63]
	v_mfma_f32_16x16x32_bf16 v[48:51], v[150:153], v[198:201], v[48:51]
	v_mfma_f32_16x16x32_bf16 v[44:47], v[166:169], v[198:201], v[44:47]
	v_mfma_f32_16x16x32_bf16 v[32:35], v[150:153], v[206:209], v[32:35]
	v_mfma_f32_16x16x32_bf16 v[28:31], v[166:169], v[206:209], v[28:31]
	v_mfma_f32_16x16x32_bf16 v[16:19], v[150:153], v[214:217], v[16:19]
	v_mfma_f32_16x16x32_bf16 v[12:15], v[166:169], v[214:217], v[12:15]
	v_mfma_f32_16x16x32_bf16 v[56:59], v[170:173], v[186:189], v[56:59]
	v_mfma_f32_16x16x32_bf16 v[52:55], v[178:181], v[186:189], v[52:55]
	v_mfma_f32_16x16x32_bf16 v[40:43], v[170:173], v[194:197], v[40:43]
	v_mfma_f32_16x16x32_bf16 v[36:39], v[178:181], v[194:197], v[36:39]
	v_mfma_f32_16x16x32_bf16 v[24:27], v[170:173], v[202:205], v[24:27]
	v_mfma_f32_16x16x32_bf16 v[20:23], v[178:181], v[202:205], v[20:23]
	v_mfma_f32_16x16x32_bf16 v[8:11], v[170:173], v[210:213], v[8:11]
	v_mfma_f32_16x16x32_bf16 v[2:5], v[178:181], v[210:213], v[4:7]
	v_mfma_f32_16x16x32_bf16 v[56:59], v[174:177], v[190:193], v[56:59]
	v_mfma_f32_16x16x32_bf16 v[52:55], v[182:185], v[190:193], v[52:55]
	v_mfma_f32_16x16x32_bf16 v[40:43], v[174:177], v[198:201], v[40:43]
	v_mfma_f32_16x16x32_bf16 v[36:39], v[182:185], v[198:201], v[36:39]
	v_mfma_f32_16x16x32_bf16 v[24:27], v[174:177], v[206:209], v[24:27]
	v_mfma_f32_16x16x32_bf16 v[20:23], v[182:185], v[206:209], v[20:23]
	v_mfma_f32_16x16x32_bf16 v[8:11], v[174:177], v[214:217], v[8:11]
	v_mfma_f32_16x16x32_bf16 v[2:5], v[182:185], v[214:217], v[2:5]
	s_barrier
	s_add_i32 s14, 0, 0x18000
	v_add_u32_e32 v1, s14, v155
	s_add_i32 s93, 0, 0x1c000
	ds_read_b128 v[146:149], v1
	ds_read_b128 v[150:153], v1 offset:1024
	ds_read_b128 v[162:165], v1 offset:2048
	ds_read_b128 v[166:169], v1 offset:3072
	v_add_u32_e32 v1, s93, v155
	ds_read_b128 v[170:173], v1
	ds_read_b128 v[174:177], v1 offset:1024
	ds_read_b128 v[178:181], v1 offset:2048
	ds_read_b128 v[182:185], v1 offset:3072
	s_add_u32 s58, s58, 0x40000
	s_addc_u32 s59, s59, 0
	s_mov_b32 m0, s63
	v_lshl_add_u64 v[6:7], s[58:59], 0, v[132:133]
	ds_read_b128 v[186:189], v159 offset:32768
	ds_read_b128 v[190:193], v159 offset:33792
	ds_read_b128 v[194:197], v159 offset:34816
	ds_read_b128 v[198:201], v159 offset:35840
	ds_read_b128 v[202:205], v159 offset:36864
	ds_read_b128 v[206:209], v159 offset:37888
	ds_read_b128 v[210:213], v159 offset:38912
	ds_read_b128 v[214:217], v159 offset:39936
	global_load_lds_dwordx4 v[6:7], off
	s_mov_b32 m0, s64
	v_lshl_add_u64 v[6:7], s[58:59], 0, v[136:137]
	global_load_lds_dwordx4 v[6:7], off
	s_waitcnt vmcnt(8)
	s_waitcnt lgkmcnt(0)
	s_barrier
	s_waitcnt lgkmcnt(0)
	s_nop 3
	v_mfma_f32_16x16x32_bf16 v[128:131], v[146:149], v[186:189], v[128:131]
	v_mfma_f32_16x16x32_bf16 v[124:127], v[162:165], v[186:189], v[124:127]
	v_mfma_f32_16x16x32_bf16 v[112:115], v[146:149], v[194:197], v[112:115]
	v_mfma_f32_16x16x32_bf16 v[108:111], v[162:165], v[194:197], v[108:111]
	v_mfma_f32_16x16x32_bf16 v[96:99], v[146:149], v[202:205], v[96:99]
	v_mfma_f32_16x16x32_bf16 v[92:95], v[162:165], v[202:205], v[92:95]
	v_mfma_f32_16x16x32_bf16 v[80:83], v[146:149], v[210:213], v[80:83]
	v_mfma_f32_16x16x32_bf16 v[76:79], v[162:165], v[210:213], v[76:79]
	v_mfma_f32_16x16x32_bf16 v[128:131], v[150:153], v[190:193], v[128:131]
	v_mfma_f32_16x16x32_bf16 v[124:127], v[166:169], v[190:193], v[124:127]
	v_mfma_f32_16x16x32_bf16 v[112:115], v[150:153], v[198:201], v[112:115]
	v_mfma_f32_16x16x32_bf16 v[108:111], v[166:169], v[198:201], v[108:111]
	v_mfma_f32_16x16x32_bf16 v[96:99], v[150:153], v[206:209], v[96:99]
	v_mfma_f32_16x16x32_bf16 v[92:95], v[166:169], v[206:209], v[92:95]
	v_mfma_f32_16x16x32_bf16 v[80:83], v[150:153], v[214:217], v[80:83]
	v_mfma_f32_16x16x32_bf16 v[76:79], v[166:169], v[214:217], v[76:79]
	v_mfma_f32_16x16x32_bf16 v[120:123], v[170:173], v[186:189], v[120:123]
	v_mfma_f32_16x16x32_bf16 v[116:119], v[178:181], v[186:189], v[116:119]
	v_mfma_f32_16x16x32_bf16 v[104:107], v[170:173], v[194:197], v[104:107]
	v_mfma_f32_16x16x32_bf16 v[100:103], v[178:181], v[194:197], v[100:103]
	v_mfma_f32_16x16x32_bf16 v[88:91], v[170:173], v[202:205], v[88:91]
	v_mfma_f32_16x16x32_bf16 v[84:87], v[178:181], v[202:205], v[84:87]
	v_mfma_f32_16x16x32_bf16 v[72:75], v[170:173], v[210:213], v[72:75]
	v_mfma_f32_16x16x32_bf16 v[68:71], v[178:181], v[210:213], v[68:71]
	v_mfma_f32_16x16x32_bf16 v[120:123], v[174:177], v[190:193], v[120:123]
	v_mfma_f32_16x16x32_bf16 v[116:119], v[182:185], v[190:193], v[116:119]
	v_mfma_f32_16x16x32_bf16 v[104:107], v[174:177], v[198:201], v[104:107]
	v_mfma_f32_16x16x32_bf16 v[100:103], v[182:185], v[198:201], v[100:103]
	v_mfma_f32_16x16x32_bf16 v[88:91], v[174:177], v[206:209], v[88:91]
	v_mfma_f32_16x16x32_bf16 v[84:87], v[182:185], v[206:209], v[84:87]
	v_mfma_f32_16x16x32_bf16 v[72:75], v[174:177], v[214:217], v[72:75]
	v_mfma_f32_16x16x32_bf16 v[68:71], v[182:185], v[214:217], v[68:71]
	s_barrier
	s_add_i32 s14, s14, s0
	v_lshl_add_u64 v[6:7], v[218:219], 0, s[24:25]
	s_mov_b32 m0, s14
	ds_read_b128 v[186:189], v159 offset:49152
	ds_read_b128 v[190:193], v159 offset:50176
	ds_read_b128 v[194:197], v159 offset:51200
	ds_read_b128 v[198:201], v159 offset:52224
	ds_read_b128 v[202:205], v159 offset:53248
	ds_read_b128 v[206:209], v159 offset:54272
	ds_read_b128 v[210:213], v159 offset:55296
	ds_read_b128 v[214:217], v159 offset:56320
	global_load_lds_dwordx4 v[6:7], off
	s_add_i32 m0, s14, 0x2000
	s_add_u32 s56, s56, 0x80080
	v_lshl_add_u64 v[6:7], v[220:221], 0, s[24:25]
	s_addc_u32 s57, s57, 0
	s_add_i32 s14, s93, s0
	global_load_lds_dwordx4 v[6:7], off
	s_mov_b32 m0, s14
	v_lshl_add_u64 v[6:7], s[56:57], 0, v[134:135]
	global_load_lds_dwordx4 v[6:7], off
	s_add_i32 m0, s14, 0x2000
	v_lshl_add_u64 v[6:7], s[56:57], 0, v[138:139]
	global_load_lds_dwordx4 v[6:7], off
	s_mov_b32 m0, s72
	v_lshl_add_u64 v[6:7], v[222:223], 0, s[24:25]
	global_load_lds_dwordx4 v[6:7], off
	s_mov_b32 m0, s73
	v_lshl_add_u64 v[6:7], v[224:225], 0, s[24:25]
	global_load_lds_dwordx4 v[6:7], off
	s_waitcnt vmcnt(8)
	s_waitcnt lgkmcnt(0)
	s_barrier
	s_waitcnt lgkmcnt(0)
	s_nop 3
	v_mfma_f32_16x16x32_bf16 v[64:67], v[146:149], v[186:189], v[64:67]
	v_mfma_f32_16x16x32_bf16 v[60:63], v[162:165], v[186:189], v[60:63]
	v_mfma_f32_16x16x32_bf16 v[48:51], v[146:149], v[194:197], v[48:51]
	v_mfma_f32_16x16x32_bf16 v[44:47], v[162:165], v[194:197], v[44:47]
	v_mfma_f32_16x16x32_bf16 v[32:35], v[146:149], v[202:205], v[32:35]
	v_mfma_f32_16x16x32_bf16 v[28:31], v[162:165], v[202:205], v[28:31]
	v_mfma_f32_16x16x32_bf16 v[16:19], v[146:149], v[210:213], v[16:19]
	v_mfma_f32_16x16x32_bf16 v[12:15], v[162:165], v[210:213], v[12:15]
	v_mfma_f32_16x16x32_bf16 v[64:67], v[150:153], v[190:193], v[64:67]
	v_mfma_f32_16x16x32_bf16 v[60:63], v[166:169], v[190:193], v[60:63]
	v_mfma_f32_16x16x32_bf16 v[48:51], v[150:153], v[198:201], v[48:51]
	v_mfma_f32_16x16x32_bf16 v[44:47], v[166:169], v[198:201], v[44:47]
	v_mfma_f32_16x16x32_bf16 v[32:35], v[150:153], v[206:209], v[32:35]
	v_mfma_f32_16x16x32_bf16 v[28:31], v[166:169], v[206:209], v[28:31]
	v_mfma_f32_16x16x32_bf16 v[16:19], v[150:153], v[214:217], v[16:19]
	v_mfma_f32_16x16x32_bf16 v[12:15], v[166:169], v[214:217], v[12:15]
	v_mfma_f32_16x16x32_bf16 v[56:59], v[170:173], v[186:189], v[56:59]
	v_mfma_f32_16x16x32_bf16 v[52:55], v[178:181], v[186:189], v[52:55]
	v_mfma_f32_16x16x32_bf16 v[40:43], v[170:173], v[194:197], v[40:43]
	v_mfma_f32_16x16x32_bf16 v[36:39], v[178:181], v[194:197], v[36:39]
	v_mfma_f32_16x16x32_bf16 v[24:27], v[170:173], v[202:205], v[24:27]
	v_mfma_f32_16x16x32_bf16 v[20:23], v[178:181], v[202:205], v[20:23]
	v_mfma_f32_16x16x32_bf16 v[6:9], v[170:173], v[210:213], v[8:11]
	v_mfma_f32_16x16x32_bf16 v[2:5], v[178:181], v[210:213], v[2:5]
	v_mfma_f32_16x16x32_bf16 v[56:59], v[174:177], v[190:193], v[56:59]
	v_mfma_f32_16x16x32_bf16 v[52:55], v[182:185], v[190:193], v[52:55]
	v_mfma_f32_16x16x32_bf16 v[40:43], v[174:177], v[198:201], v[40:43]
	v_mfma_f32_16x16x32_bf16 v[36:39], v[182:185], v[198:201], v[36:39]
	v_mfma_f32_16x16x32_bf16 v[24:27], v[174:177], v[206:209], v[24:27]
	v_mfma_f32_16x16x32_bf16 v[20:23], v[182:185], v[206:209], v[20:23]
	v_mfma_f32_16x16x32_bf16 v[8:11], v[174:177], v[214:217], v[6:9]
	v_mfma_f32_16x16x32_bf16 v[4:7], v[182:185], v[214:217], v[2:5]
	s_barrier
	s_add_i32 s14, s92, 2
	s_add_u32 s54, s54, 0x100
	s_addc_u32 s55, s55, 0
	s_add_u32 s90, s90, 0x100
	s_addc_u32 s91, s91, 0
	s_cmp_gt_u32 s92, 29
	s_mov_b32 s92, s14
	s_cbranch_scc1 .LBB0_554

.LBB0_658:
	v_add_u32_e32 v1, s61, v201
	ds_read_b128 v[102:105], v1
	ds_read_b128 v[106:109], v1 offset:1024
	ds_read_b128 v[110:113], v1 offset:2048
	ds_read_b128 v[114:117], v1 offset:3072
	v_add_u32_e32 v1, s62, v201
	ds_read_b128 v[118:121], v1
	ds_read_b128 v[156:159], v1 offset:1024
	ds_read_b128 v[160:163], v1 offset:2048
	ds_read_b128 v[164:167], v1 offset:3072
	s_and_b64 s[48:49], exec, s[48:49]
	s_cselect_b32 s49, s27, s78
	s_cselect_b32 s48, s29, s73
	s_add_u32 s80, s80, 0x40000
	s_addc_u32 s81, s81, 0
	v_lshl_add_u64 v[2:3], s[80:81], 0, v[178:179]
	s_add_i32 m0, s41, 0xc000
	ds_read_b128 v[168:171], v207
	ds_read_b128 v[184:187], v207 offset:1024
	ds_read_b128 v[188:191], v207 offset:2048
	ds_read_b128 v[192:195], v207 offset:3072
	ds_read_b128 v[208:211], v207 offset:4096
	ds_read_b128 v[212:215], v207 offset:5120
	ds_read_b128 v[216:219], v207 offset:6144
	ds_read_b128 v[220:223], v207 offset:7168
	global_load_lds_dwordx4 v[2:3], off
	s_add_i32 m0, s41, 0xe000
	v_lshl_add_u64 v[2:3], s[80:81], 0, v[174:175]
	global_load_lds_dwordx4 v[2:3], off
	s_waitcnt vmcnt(8)
	s_waitcnt lgkmcnt(0)
	s_barrier
	s_waitcnt lgkmcnt(0)
	s_nop 3
	v_mfma_f32_16x16x32_bf16 v[152:155], v[102:105], v[168:171], v[152:155]
	v_mfma_f32_16x16x32_bf16 v[148:151], v[110:113], v[168:171], v[148:151]
	v_mfma_f32_16x16x32_bf16 v[144:147], v[102:105], v[188:191], v[144:147]
	v_mfma_f32_16x16x32_bf16 v[140:143], v[110:113], v[188:191], v[140:143]
	v_mfma_f32_16x16x32_bf16 v[136:139], v[102:105], v[208:211], v[136:139]
	v_mfma_f32_16x16x32_bf16 v[132:135], v[110:113], v[208:211], v[132:135]
	v_mfma_f32_16x16x32_bf16 v[128:131], v[102:105], v[216:219], v[128:131]
	v_mfma_f32_16x16x32_bf16 v[122:125], v[110:113], v[216:219], v[124:127]
	v_mfma_f32_16x16x32_bf16 v[152:155], v[106:109], v[184:187], v[152:155]
	v_mfma_f32_16x16x32_bf16 v[148:151], v[114:117], v[184:187], v[148:151]
	v_mfma_f32_16x16x32_bf16 v[144:147], v[106:109], v[192:195], v[144:147]
	v_mfma_f32_16x16x32_bf16 v[140:143], v[114:117], v[192:195], v[140:143]
	v_mfma_f32_16x16x32_bf16 v[136:139], v[106:109], v[212:215], v[136:139]
	v_mfma_f32_16x16x32_bf16 v[132:135], v[114:117], v[212:215], v[132:135]
	v_mfma_f32_16x16x32_bf16 v[128:131], v[106:109], v[220:223], v[128:131]
	v_mfma_f32_16x16x32_bf16 v[122:125], v[114:117], v[220:223], v[122:125]
	v_mfma_f32_16x16x32_bf16 v[64:67], v[118:121], v[168:171], v[64:67]
	v_mfma_f32_16x16x32_bf16 v[60:63], v[160:163], v[168:171], v[60:63]
	v_mfma_f32_16x16x32_bf16 v[56:59], v[118:121], v[188:191], v[56:59]
	v_mfma_f32_16x16x32_bf16 v[52:55], v[160:163], v[188:191], v[52:55]
	v_mfma_f32_16x16x32_bf16 v[48:51], v[118:121], v[208:211], v[48:51]
	v_mfma_f32_16x16x32_bf16 v[44:47], v[160:163], v[208:211], v[44:47]
	v_mfma_f32_16x16x32_bf16 v[40:43], v[118:121], v[216:219], v[40:43]
	v_mfma_f32_16x16x32_bf16 v[36:39], v[160:163], v[216:219], v[36:39]
	v_mfma_f32_16x16x32_bf16 v[64:67], v[156:159], v[184:187], v[64:67]
	v_mfma_f32_16x16x32_bf16 v[60:63], v[164:167], v[184:187], v[60:63]
	v_mfma_f32_16x16x32_bf16 v[56:59], v[156:159], v[192:195], v[56:59]
	v_mfma_f32_16x16x32_bf16 v[52:55], v[164:167], v[192:195], v[52:55]
	v_mfma_f32_16x16x32_bf16 v[48:51], v[156:159], v[212:215], v[48:51]
	v_mfma_f32_16x16x32_bf16 v[44:47], v[164:167], v[212:215], v[44:47]
	v_mfma_f32_16x16x32_bf16 v[40:43], v[156:159], v[220:223], v[40:43]
	v_mfma_f32_16x16x32_bf16 v[36:39], v[164:167], v[220:223], v[36:39]
	s_barrier
	s_add_i32 s6, s61, s53
	v_lshl_add_u64 v[196:197], s[48:49], 0, v[176:177]
	s_mov_b32 m0, s6
	ds_read_b128 v[168:171], v207 offset:16384
	ds_read_b128 v[184:187], v207 offset:17408
	ds_read_b128 v[188:191], v207 offset:18432
	ds_read_b128 v[192:195], v207 offset:19456
	ds_read_b128 v[208:211], v207 offset:20480
	ds_read_b128 v[212:215], v207 offset:21504
	ds_read_b128 v[216:219], v207 offset:22528
	ds_read_b128 v[220:223], v207 offset:23552
	global_load_lds_dwordx4 v[196:197], off
	s_add_i32 m0, s6, 0x2000
	s_add_u32 s80, s48, 0x80000
	v_lshl_add_u64 v[224:225], s[48:49], 0, v[172:173]
	s_addc_u32 s81, s49, 0
	s_add_i32 s6, s62, s53
	global_load_lds_dwordx4 v[224:225], off
	v_lshl_add_u64 v[2:3], s[80:81], 0, v[176:177]
	s_mov_b32 m0, s6
	v_lshl_add_u64 v[226:227], s[50:51], 0, v[178:179]
	global_load_lds_dwordx4 v[2:3], off
	v_lshl_add_u64 v[2:3], s[80:81], 0, v[172:173]
	s_add_i32 m0, s6, 0x2000
	v_lshl_add_u64 v[228:229], s[50:51], 0, v[174:175]
	global_load_lds_dwordx4 v[2:3], off
	s_mov_b32 m0, s41
	s_nop 0
	global_load_lds_dwordx4 v[226:227], off
	s_mov_b32 m0, s56
	s_nop 0
	global_load_lds_dwordx4 v[228:229], off
	s_waitcnt vmcnt(8)
	s_waitcnt lgkmcnt(0)
	s_barrier
	s_waitcnt lgkmcnt(0)
	s_nop 3
	v_mfma_f32_16x16x32_bf16 v[96:99], v[102:105], v[168:171], v[96:99]
	v_mfma_f32_16x16x32_bf16 v[92:95], v[110:113], v[168:171], v[92:95]
	v_mfma_f32_16x16x32_bf16 v[88:91], v[102:105], v[188:191], v[88:91]
	v_mfma_f32_16x16x32_bf16 v[84:87], v[110:113], v[188:191], v[84:87]
	v_mfma_f32_16x16x32_bf16 v[80:83], v[102:105], v[208:211], v[80:83]
	v_mfma_f32_16x16x32_bf16 v[76:79], v[110:113], v[208:211], v[76:79]
	v_mfma_f32_16x16x32_bf16 v[72:75], v[102:105], v[216:219], v[72:75]
	v_mfma_f32_16x16x32_bf16 v[68:71], v[110:113], v[216:219], v[68:71]
	v_mfma_f32_16x16x32_bf16 v[96:99], v[106:109], v[184:187], v[96:99]
	v_mfma_f32_16x16x32_bf16 v[92:95], v[114:117], v[184:187], v[92:95]
	v_mfma_f32_16x16x32_bf16 v[88:91], v[106:109], v[192:195], v[88:91]
	v_mfma_f32_16x16x32_bf16 v[84:87], v[114:117], v[192:195], v[84:87]
	v_mfma_f32_16x16x32_bf16 v[80:83], v[106:109], v[212:215], v[80:83]
	v_mfma_f32_16x16x32_bf16 v[76:79], v[114:117], v[212:215], v[76:79]
	v_mfma_f32_16x16x32_bf16 v[72:75], v[106:109], v[220:223], v[72:75]
	v_mfma_f32_16x16x32_bf16 v[68:71], v[114:117], v[220:223], v[68:71]
	v_mfma_f32_16x16x32_bf16 v[32:35], v[118:121], v[168:171], v[32:35]
	v_mfma_f32_16x16x32_bf16 v[28:31], v[160:163], v[168:171], v[28:31]
	v_mfma_f32_16x16x32_bf16 v[24:27], v[118:121], v[188:191], v[24:27]
	v_mfma_f32_16x16x32_bf16 v[20:23], v[160:163], v[188:191], v[20:23]
	v_mfma_f32_16x16x32_bf16 v[16:19], v[118:121], v[208:211], v[16:19]
	v_mfma_f32_16x16x32_bf16 v[12:15], v[160:163], v[208:211], v[12:15]
	v_mfma_f32_16x16x32_bf16 v[8:11], v[118:121], v[216:219], v[8:11]
	v_mfma_f32_16x16x32_bf16 v[2:5], v[160:163], v[216:219], v[4:7]
	v_mfma_f32_16x16x32_bf16 v[32:35], v[156:159], v[184:187], v[32:35]
	v_mfma_f32_16x16x32_bf16 v[28:31], v[164:167], v[184:187], v[28:31]
	v_mfma_f32_16x16x32_bf16 v[24:27], v[156:159], v[192:195], v[24:27]
	v_mfma_f32_16x16x32_bf16 v[20:23], v[164:167], v[192:195], v[20:23]
	v_mfma_f32_16x16x32_bf16 v[16:19], v[156:159], v[212:215], v[16:19]
	v_mfma_f32_16x16x32_bf16 v[12:15], v[164:167], v[212:215], v[12:15]
	v_mfma_f32_16x16x32_bf16 v[8:11], v[156:159], v[220:223], v[8:11]
	v_mfma_f32_16x16x32_bf16 v[2:5], v[164:167], v[220:223], v[2:5]
	s_barrier
	s_add_i32 s6, 0, 0x18000
	v_add_u32_e32 v1, s6, v201
	s_add_i32 s80, 0, 0x1c000
	ds_read_b128 v[102:105], v1
	ds_read_b128 v[106:109], v1 offset:1024
	ds_read_b128 v[110:113], v1 offset:2048
	ds_read_b128 v[114:117], v1 offset:3072
	v_add_u32_e32 v1, s80, v201
	ds_read_b128 v[118:121], v1
	ds_read_b128 v[156:159], v1 offset:1024
	ds_read_b128 v[160:163], v1 offset:2048
	ds_read_b128 v[164:167], v1 offset:3072
	s_add_u32 s50, s50, 0x40000
	s_addc_u32 s51, s51, 0
	s_mov_b32 m0, s57
	v_lshl_add_u64 v[6:7], s[50:51], 0, v[178:179]
	ds_read_b128 v[168:171], v207 offset:32768
	ds_read_b128 v[184:187], v207 offset:33792
	ds_read_b128 v[188:191], v207 offset:34816
	ds_read_b128 v[192:195], v207 offset:35840
	ds_read_b128 v[208:211], v207 offset:36864
	ds_read_b128 v[212:215], v207 offset:37888
	ds_read_b128 v[216:219], v207 offset:38912
	ds_read_b128 v[220:223], v207 offset:39936
	global_load_lds_dwordx4 v[6:7], off
	s_mov_b32 m0, s58
	v_lshl_add_u64 v[6:7], s[50:51], 0, v[174:175]
	global_load_lds_dwordx4 v[6:7], off
	s_waitcnt vmcnt(8)
	s_waitcnt lgkmcnt(0)
	s_barrier
	s_waitcnt lgkmcnt(0)
	s_nop 3
	v_mfma_f32_16x16x32_bf16 v[152:155], v[102:105], v[168:171], v[152:155]
	v_mfma_f32_16x16x32_bf16 v[148:151], v[110:113], v[168:171], v[148:151]
	v_mfma_f32_16x16x32_bf16 v[144:147], v[102:105], v[188:191], v[144:147]
	v_mfma_f32_16x16x32_bf16 v[140:143], v[110:113], v[188:191], v[140:143]
	v_mfma_f32_16x16x32_bf16 v[136:139], v[102:105], v[208:211], v[136:139]
	v_mfma_f32_16x16x32_bf16 v[132:135], v[110:113], v[208:211], v[132:135]
	v_mfma_f32_16x16x32_bf16 v[126:129], v[102:105], v[216:219], v[128:131]
	v_mfma_f32_16x16x32_bf16 v[122:125], v[110:113], v[216:219], v[122:125]
	v_mfma_f32_16x16x32_bf16 v[152:155], v[106:109], v[184:187], v[152:155]
	v_mfma_f32_16x16x32_bf16 v[148:151], v[114:117], v[184:187], v[148:151]
	v_mfma_f32_16x16x32_bf16 v[144:147], v[106:109], v[192:195], v[144:147]
	v_mfma_f32_16x16x32_bf16 v[140:143], v[114:117], v[192:195], v[140:143]
	v_mfma_f32_16x16x32_bf16 v[136:139], v[106:109], v[212:215], v[136:139]
	v_mfma_f32_16x16x32_bf16 v[132:135], v[114:117], v[212:215], v[132:135]
	v_mfma_f32_16x16x32_bf16 v[128:131], v[106:109], v[220:223], v[126:129]
	v_mfma_f32_16x16x32_bf16 v[124:127], v[114:117], v[220:223], v[122:125]
	v_mfma_f32_16x16x32_bf16 v[64:67], v[118:121], v[168:171], v[64:67]
	v_mfma_f32_16x16x32_bf16 v[60:63], v[160:163], v[168:171], v[60:63]
	v_mfma_f32_16x16x32_bf16 v[56:59], v[118:121], v[188:191], v[56:59]
	v_mfma_f32_16x16x32_bf16 v[52:55], v[160:163], v[188:191], v[52:55]
	v_mfma_f32_16x16x32_bf16 v[48:51], v[118:121], v[208:211], v[48:51]
	v_mfma_f32_16x16x32_bf16 v[44:47], v[160:163], v[208:211], v[44:47]
	v_mfma_f32_16x16x32_bf16 v[40:43], v[118:121], v[216:219], v[40:43]
	v_mfma_f32_16x16x32_bf16 v[36:39], v[160:163], v[216:219], v[36:39]
	v_mfma_f32_16x16x32_bf16 v[64:67], v[156:159], v[184:187], v[64:67]
	v_mfma_f32_16x16x32_bf16 v[60:63], v[164:167], v[184:187], v[60:63]
	v_mfma_f32_16x16x32_bf16 v[56:59], v[156:159], v[192:195], v[56:59]
	v_mfma_f32_16x16x32_bf16 v[52:55], v[164:167], v[192:195], v[52:55]
	v_mfma_f32_16x16x32_bf16 v[48:51], v[156:159], v[212:215], v[48:51]
	v_mfma_f32_16x16x32_bf16 v[44:47], v[164:167], v[212:215], v[44:47]
	v_mfma_f32_16x16x32_bf16 v[40:43], v[156:159], v[220:223], v[40:43]
	v_mfma_f32_16x16x32_bf16 v[36:39], v[164:167], v[220:223], v[36:39]
	s_barrier
	s_add_i32 s6, s6, s53
	v_lshl_add_u64 v[6:7], v[196:197], 0, s[14:15]
	s_mov_b32 m0, s6
	ds_read_b128 v[168:171], v207 offset:49152
	ds_read_b128 v[184:187], v207 offset:50176
	ds_read_b128 v[188:191], v207 offset:51200
	ds_read_b128 v[192:195], v207 offset:52224
	ds_read_b128 v[208:211], v207 offset:53248
	ds_read_b128 v[212:215], v207 offset:54272
	ds_read_b128 v[216:219], v207 offset:55296
	ds_read_b128 v[220:223], v207 offset:56320
	global_load_lds_dwordx4 v[6:7], off
	s_add_i32 m0, s6, 0x2000
	s_add_u32 s48, s48, 0x80080
	v_lshl_add_u64 v[6:7], v[224:225], 0, s[14:15]
	s_addc_u32 s49, s49, 0
	s_add_i32 s6, s80, s53
	global_load_lds_dwordx4 v[6:7], off
	s_mov_b32 m0, s6
	v_lshl_add_u64 v[6:7], s[48:49], 0, v[176:177]
	global_load_lds_dwordx4 v[6:7], off
	s_add_i32 m0, s6, 0x2000
	v_lshl_add_u64 v[6:7], s[48:49], 0, v[172:173]
	global_load_lds_dwordx4 v[6:7], off
	s_mov_b32 m0, s59
	v_lshl_add_u64 v[6:7], v[226:227], 0, s[14:15]
	global_load_lds_dwordx4 v[6:7], off
	s_mov_b32 m0, s60
	v_lshl_add_u64 v[6:7], v[228:229], 0, s[14:15]
	global_load_lds_dwordx4 v[6:7], off
	s_waitcnt vmcnt(8)
	s_waitcnt lgkmcnt(0)
	s_barrier
	s_waitcnt lgkmcnt(0)
	s_nop 3
	v_mfma_f32_16x16x32_bf16 v[96:99], v[102:105], v[168:171], v[96:99]
	v_mfma_f32_16x16x32_bf16 v[92:95], v[110:113], v[168:171], v[92:95]
	v_mfma_f32_16x16x32_bf16 v[88:91], v[102:105], v[188:191], v[88:91]
	v_mfma_f32_16x16x32_bf16 v[84:87], v[110:113], v[188:191], v[84:87]
	v_mfma_f32_16x16x32_bf16 v[80:83], v[102:105], v[208:211], v[80:83]
	v_mfma_f32_16x16x32_bf16 v[76:79], v[110:113], v[208:211], v[76:79]
	v_mfma_f32_16x16x32_bf16 v[72:75], v[102:105], v[216:219], v[72:75]
	v_mfma_f32_16x16x32_bf16 v[68:71], v[110:113], v[216:219], v[68:71]
	v_mfma_f32_16x16x32_bf16 v[96:99], v[106:109], v[184:187], v[96:99]
	v_mfma_f32_16x16x32_bf16 v[92:95], v[114:117], v[184:187], v[92:95]
	v_mfma_f32_16x16x32_bf16 v[88:91], v[106:109], v[192:195], v[88:91]
	v_mfma_f32_16x16x32_bf16 v[84:87], v[114:117], v[192:195], v[84:87]
	v_mfma_f32_16x16x32_bf16 v[80:83], v[106:109], v[212:215], v[80:83]
	v_mfma_f32_16x16x32_bf16 v[76:79], v[114:117], v[212:215], v[76:79]
	v_mfma_f32_16x16x32_bf16 v[72:75], v[106:109], v[220:223], v[72:75]
	v_mfma_f32_16x16x32_bf16 v[68:71], v[114:117], v[220:223], v[68:71]
	v_mfma_f32_16x16x32_bf16 v[32:35], v[118:121], v[168:171], v[32:35]
	v_mfma_f32_16x16x32_bf16 v[28:31], v[160:163], v[168:171], v[28:31]
	v_mfma_f32_16x16x32_bf16 v[24:27], v[118:121], v[188:191], v[24:27]
	v_mfma_f32_16x16x32_bf16 v[20:23], v[160:163], v[188:191], v[20:23]
	v_mfma_f32_16x16x32_bf16 v[16:19], v[118:121], v[208:211], v[16:19]
	v_mfma_f32_16x16x32_bf16 v[12:15], v[160:163], v[208:211], v[12:15]
	v_mfma_f32_16x16x32_bf16 v[6:9], v[118:121], v[216:219], v[8:11]
	v_mfma_f32_16x16x32_bf16 v[2:5], v[160:163], v[216:219], v[2:5]
	v_mfma_f32_16x16x32_bf16 v[32:35], v[156:159], v[184:187], v[32:35]
	v_mfma_f32_16x16x32_bf16 v[28:31], v[164:167], v[184:187], v[28:31]
	v_mfma_f32_16x16x32_bf16 v[24:27], v[156:159], v[192:195], v[24:27]
	v_mfma_f32_16x16x32_bf16 v[20:23], v[164:167], v[192:195], v[20:23]
	v_mfma_f32_16x16x32_bf16 v[16:19], v[156:159], v[212:215], v[16:19]
	v_mfma_f32_16x16x32_bf16 v[12:15], v[164:167], v[212:215], v[12:15]
	v_mfma_f32_16x16x32_bf16 v[8:11], v[156:159], v[220:223], v[6:9]
	v_mfma_f32_16x16x32_bf16 v[4:7], v[164:167], v[220:223], v[2:5]
	s_barrier
	s_add_i32 s6, s79, 2
	s_add_u32 s44, s44, 0x100
	s_addc_u32 s45, s45, 0
	s_add_u32 s73, s73, 0x100
	s_addc_u32 s78, s78, 0
	s_cmp_gt_u32 s79, 29
	s_cbranch_scc1 .LBB0_660
	s_mov_b32 s79, s6
	s_cmp_lg_u32 s79, 16
	s_cbranch_scc0 .LBB0_652
	s_branch .LBB0_653
